# GLA pass B o/state-update region: LDS reads batched into two ping-pong register sets behind counted lgkmcnt waits (same MFMA chains, same order)
# baseline (speedup 1.0000x reference)
; #define LAS __attribute__((address_space(3)))
; #define LDS_SYNC() do { asm volatile("s_waitcnt lgkmcnt(0)" ::: "memory"); __builtin_amdgcn_s_barrier(); asm volatile("" ::: "memory"); } while (0)
; template <class F>
; __device__ __forceinline__ void small_gemm_ks(LAS unsigned char* lds, const bf16_t* A, int lda, const bf16_t* Bt, int ldb, int K, int N, int a_grp_cols, int bx, int G, int tid, const F& f) {
;     ...
;     for (int t = bx; t < ntiles; t += G) {
;         const int row0 = MP + (t / ntn) * 32 + wm * 16, n0 = (t % ntn) * 64 + wn * 32;
;         const bf16_t* ap = A + (size_t)(row0 + c) * lda + (n0 >> 8) * a_grp_cols + kh * KH + 8 * g;
;         const bf16_t* bp = Bt + (size_t)(n0 + c) * ldb + kh * KH + 8 * g;
;         f32x4 acc[2] = {(f32x4){0.f, 0.f, 0.f, 0.f}, (f32x4){0.f, 0.f, 0.f, 0.f}};
; #pragma unroll 8
;         for (int k0 = 0; k0 < KH; k0 += 32) { const bf16x8 av = *(const bf16x8*)(ap + k0);
; #pragma unroll
;             for (int nt = 0; nt < 2; ++nt) { const bf16x8 bv = *(const bf16x8*)(bp + (size_t)nt * 16 * ldb + k0); acc[nt] = __builtin_amdgcn_mfma_f32_16x16x32_bf16(av, bv, acc[nt], 0, 0, 0); } }
;         if (kh == 1) { *(LAS f32x4*)(lds + ((wq * 2 + 0) * 64 + lane) * 16) = acc[0]; *(LAS f32x4*)(lds + ((wq * 2 + 1) * 64 + lane) * 16) = acc[1]; }
;         LDS_SYNC();
.Lsg_pool_tile:
	s_lshr_b32 s82, s81, 4
	s_and_b32 s83, s81, 15
	s_lshl_b32 s82, s82, 5
	s_add_i32 s82, s82, 0x4000
	s_lshl_b32 s83, s83, 6
	s_lshl_b32 s59, s80, 3
	s_add_i32 s59, s59, s82
	s_mul_i32 s60, s59, 2048
	s_mul_hi_u32 s61, s59, 2048
	s_mul_i32 s62, s70, 256
	s_add_u32 s60, s60, s62
	s_addc_u32 s61, s61, 0
	s_lshr_b32 s62, s83, 8
	s_lshl_b32 s62, s62, 9
	s_add_u32 s60, s60, s62
	s_addc_u32 s61, s61, 0
	s_add_u32 s60, s60, s54
	s_addc_u32 s61, s61, s55
	s_add_u32 s60, s60, 0x9900000
	s_addc_u32 s61, s61, 0
	v_lshl_add_u64 v[110:111], s[60:61], 0, v[90:91]
	s_lshl_b32 s59, s80, 4
	s_add_i32 s59, s59, s83
	s_mul_i32 s60, s59, 512
	s_mul_i32 s62, s70, 256
	s_add_u32 s60, s60, s62
	s_add_u32 s60, s60, s54
	s_addc_u32 s61, s55, 0
	s_add_u32 s60, s60, 0x100000
	s_addc_u32 s61, s61, 0
	v_lshl_add_u64 v[112:113], s[60:61], 0, v[92:93]
	s_add_u32 s60, s60, 4096
	s_addc_u32 s61, s61, 0
	v_lshl_add_u64 v[114:115], s[60:61], 0, v[92:93]
	s_lshl_b32 s59, s83, 2
	v_add_u32_e32 v116, s59, v108
	s_waitcnt lgkmcnt(0)
	global_load_dword v117, v116, s[92:93]
	global_load_dword v118, v116, s[92:93] offset:64
	v_mov_b32_e32 v120, 0
	v_mov_b32_e32 v121, 0
	v_mov_b32_e32 v122, 0
	v_mov_b32_e32 v123, 0
	v_mov_b32_e32 v124, 0
	v_mov_b32_e32 v125, 0
	v_mov_b32_e32 v126, 0
	v_mov_b32_e32 v127, 0
	s_add_i32 m0, s76, 0
	s_nop 0
	global_load_lds_dwordx4 v[110:111], off
	v_lshl_add_u64 v[110:111], v[110:111], 0, s[78:79]
	s_add_i32 m0, s77, 0
	s_nop 0
	global_load_lds_dwordx4 v[112:113], off
	v_lshl_add_u64 v[112:113], v[112:113], 0, s[78:79]
	s_add_i32 m0, s77, 1024
	s_nop 0
	global_load_lds_dwordx4 v[114:115], off
	v_lshl_add_u64 v[114:115], v[114:115], 0, s[78:79]
	s_add_i32 m0, s76, 24576
	s_nop 0
	global_load_lds_dwordx4 v[110:111], off
	v_lshl_add_u64 v[110:111], v[110:111], 0, s[78:79]
	s_add_i32 m0, s77, 24576
	s_nop 0
	global_load_lds_dwordx4 v[112:113], off
	v_lshl_add_u64 v[112:113], v[112:113], 0, s[78:79]
	s_add_i32 m0, s77, 25600
	s_nop 0
	global_load_lds_dwordx4 v[114:115], off
	v_lshl_add_u64 v[114:115], v[114:115], 0, s[78:79]
	s_waitcnt vmcnt(3)
	s_barrier
	ds_read_b128 v[128:131], v96
	ds_read_b128 v[136:139], v101 offset:0
	ds_read_b128 v[144:147], v101 offset:2048
	ds_read_b128 v[132:135], v188
	ds_read_b128 v[140:143], v193 offset:0
	ds_read_b128 v[148:151], v193 offset:2048
	s_waitcnt lgkmcnt(3)
	v_mfma_f32_16x16x32_bf16 v[120:123], v[128:131], v[136:139], v[120:123]
	v_mfma_f32_16x16x32_bf16 v[124:127], v[128:131], v[144:147], v[124:127]
	s_waitcnt lgkmcnt(0)
	v_mfma_f32_16x16x32_bf16 v[120:123], v[132:135], v[140:143], v[120:123]
	v_mfma_f32_16x16x32_bf16 v[124:127], v[132:135], v[148:151], v[124:127]
	s_waitcnt vmcnt(0)
	s_barrier
	ds_read_b128 v[152:155], v97
	ds_read_b128 v[160:163], v102 offset:0
	ds_read_b128 v[168:171], v102 offset:2048
	ds_read_b128 v[156:159], v189
	ds_read_b128 v[164:167], v194 offset:0
	ds_read_b128 v[172:175], v194 offset:2048
	s_waitcnt lgkmcnt(3)
	v_mfma_f32_16x16x32_bf16 v[120:123], v[152:155], v[160:163], v[120:123]
	v_mfma_f32_16x16x32_bf16 v[124:127], v[152:155], v[168:171], v[124:127]
	s_waitcnt lgkmcnt(0)
	v_mfma_f32_16x16x32_bf16 v[120:123], v[156:159], v[164:167], v[120:123]
	v_mfma_f32_16x16x32_bf16 v[124:127], v[156:159], v[172:175], v[124:127]
	s_barrier
	s_lshl_b32 s59, s82, 11
	s_lshl_b32 s62, s83, 1
	s_add_i32 s59, s59, s62
	s_add_u32 s60, s54, s59
	s_addc_u32 s61, s55, 0
	s_add_u32 s60, s60, 0x5700000
	s_addc_u32 s61, s61, 0
	v_lshl_add_u64 v[176:177], s[60:61], 0, v[106:107]
	s_mov_b32 s62, 0x1000
	s_mov_b32 s63, 0
	v_lshl_add_u64 v[178:179], v[176:177], 0, s[62:63]
	s_cmp_eq_u32 s70, 0
	s_cbranch_scc1 .Lsg_pool_lo
	s_nop 4
	ds_write_b128 v109, v[120:123]
	ds_write_b128 v109, v[124:127] offset:1024
	s_waitcnt lgkmcnt(0)
	s_barrier
	s_branch .Lsg_pool_done

; #define LDS_SYNC() do { asm volatile("s_waitcnt lgkmcnt(0)" ::: "memory"); __builtin_amdgcn_s_barrier(); asm volatile("" ::: "memory"); } while (0)
; template <class F>
; __device__ __forceinline__ void small_gemm_ks(LAS unsigned char* lds, const bf16_t* A, int lda, const bf16_t* Bt, int ldb, int K, int N, int a_grp_cols, int bx, int G, int tid, const F& f) {
;     ...
;         LDS_SYNC();
;     }
.Lsg_pool_done:
	s_waitcnt lgkmcnt(0)
	s_barrier
	s_waitcnt vmcnt(0)
	s_add_i32 s81, s81, s56
	s_cmpk_lt_i32 s81, 0x100
	s_cbranch_scc1 .Lsg_pool_tile

; template <class F>
; __device__ __forceinline__ void small_gemm_ks(LAS unsigned char* lds, const bf16_t* A, int lda, const bf16_t* Bt, int ldb, int K, int N, int a_grp_cols, int bx, int G, int tid, const F& f) {
;     ...
;     for (int t = bx; t < ntiles; t += G) {
;         const int row0 = MP + (t / ntn) * 32 + wm * 16, n0 = (t % ntn) * 64 + wn * 32;
;         const bf16_t* ap = A + (size_t)(row0 + c) * lda + (n0 >> 8) * a_grp_cols + kh * KH + 8 * g;
;         const bf16_t* bp = Bt + (size_t)(n0 + c) * ldb + kh * KH + 8 * g;
;         f32x4 acc[2] = {(f32x4){0.f, 0.f, 0.f, 0.f}, (f32x4){0.f, 0.f, 0.f, 0.f}};
; #pragma unroll 8
;         for (int k0 = 0; k0 < KH; k0 += 32) { const bf16x8 av = *(const bf16x8*)(ap + k0);
; #pragma unroll
;             for (int nt = 0; nt < 2; ++nt) { const bf16x8 bv = *(const bf16x8*)(bp + (size_t)nt * 16 * ldb + k0); acc[nt] = __builtin_amdgcn_mfma_f32_16x16x32_bf16(av, bv, acc[nt], 0, 0, 0); } }
.Lsg_dn0_tile:
	s_lshr_b32 s82, s81, 4
	s_and_b32 s83, s81, 15
	s_lshl_b32 s82, s82, 5
	s_add_i32 s82, s82, 0x4000
	s_lshl_b32 s83, s83, 6
	s_lshl_b32 s59, s80, 3
	s_add_i32 s59, s59, s82
	s_mul_i32 s60, s59, 5632
	s_mul_hi_u32 s61, s59, 5632
	s_mul_i32 s62, s70, 2816
	s_add_u32 s60, s60, s62
	s_addc_u32 s61, s61, 0
	s_add_u32 s60, s60, s54
	s_addc_u32 s61, s61, s55
	s_add_u32 s60, s60, 0x9900000
	s_addc_u32 s61, s61, 0
	v_lshl_add_u64 v[110:111], s[60:61], 0, v[90:91]
	s_lshl_b32 s59, s80, 4
	s_add_i32 s59, s59, s83
	s_mul_i32 s60, s59, 5632
	s_mul_i32 s62, s70, 2816
	s_add_u32 s60, s60, s62
	s_add_u32 s60, s60, s54
	s_addc_u32 s61, s55, 0
	s_add_u32 s60, s60, 0xc80000
	s_addc_u32 s61, s61, 0
	v_lshl_add_u64 v[112:113], s[60:61], 0, v[92:93]
	s_add_u32 s60, s60, 45056
	s_addc_u32 s61, s61, 0
	v_lshl_add_u64 v[114:115], s[60:61], 0, v[92:93]
	v_mov_b32_e32 v120, 0
	v_mov_b32_e32 v121, 0
	v_mov_b32_e32 v122, 0
	v_mov_b32_e32 v123, 0
	v_mov_b32_e32 v124, 0
	v_mov_b32_e32 v125, 0
	v_mov_b32_e32 v126, 0
	v_mov_b32_e32 v127, 0
	s_add_i32 m0, s76, 0
	s_nop 0
	global_load_lds_dwordx4 v[110:111], off
	v_lshl_add_u64 v[110:111], v[110:111], 0, s[78:79]
	s_add_i32 m0, s77, 0
	s_nop 0
	global_load_lds_dwordx4 v[112:113], off
	v_lshl_add_u64 v[112:113], v[112:113], 0, s[78:79]
	s_add_i32 m0, s77, 1024
	s_nop 0
	global_load_lds_dwordx4 v[114:115], off
	v_lshl_add_u64 v[114:115], v[114:115], 0, s[78:79]
	s_add_i32 m0, s76, 24576
	s_nop 0
	global_load_lds_dwordx4 v[110:111], off
	v_lshl_add_u64 v[110:111], v[110:111], 0, s[78:79]
	s_add_i32 m0, s77, 24576
	s_nop 0
	global_load_lds_dwordx4 v[112:113], off
	v_lshl_add_u64 v[112:113], v[112:113], 0, s[78:79]
	s_add_i32 m0, s77, 25600
	s_nop 0
	global_load_lds_dwordx4 v[114:115], off
	v_lshl_add_u64 v[114:115], v[114:115], 0, s[78:79]
	s_add_i32 m0, s76, 49152
	s_nop 0
	global_load_lds_dwordx4 v[110:111], off
	v_lshl_add_u64 v[110:111], v[110:111], 0, s[78:79]
	s_add_i32 m0, s77, 49152
	s_nop 0
	global_load_lds_dwordx4 v[112:113], off
	v_lshl_add_u64 v[112:113], v[112:113], 0, s[78:79]
	s_add_i32 m0, s77, 50176
	s_nop 0
	global_load_lds_dwordx4 v[114:115], off
	v_lshl_add_u64 v[114:115], v[114:115], 0, s[78:79]
	s_add_i32 m0, s76, 73728
	s_nop 0
	global_load_lds_dwordx4 v[110:111], off
	v_lshl_add_u64 v[110:111], v[110:111], 0, s[78:79]
	s_add_i32 m0, s77, 73728
	s_nop 0
	global_load_lds_dwordx4 v[112:113], off
	v_lshl_add_u64 v[112:113], v[112:113], 0, s[78:79]
	s_add_i32 m0, s77, 74752
	s_nop 0
	global_load_lds_dwordx4 v[114:115], off
	v_lshl_add_u64 v[114:115], v[114:115], 0, s[78:79]
	s_waitcnt vmcnt(9)
	s_barrier
	ds_read_b128 v[128:131], v96
	ds_read_b128 v[136:139], v101 offset:0
	ds_read_b128 v[144:147], v101 offset:2048
	ds_read_b128 v[132:135], v188
	ds_read_b128 v[140:143], v193 offset:0
	ds_read_b128 v[148:151], v193 offset:2048
	s_add_i32 m0, s76, 98304
	s_nop 0
	global_load_lds_dwordx4 v[110:111], off
	v_lshl_add_u64 v[110:111], v[110:111], 0, s[78:79]
	s_add_i32 m0, s77, 98304
	s_nop 0
	global_load_lds_dwordx4 v[112:113], off
	v_lshl_add_u64 v[112:113], v[112:113], 0, s[78:79]
	s_add_i32 m0, s77, 99328
	s_nop 0
	global_load_lds_dwordx4 v[114:115], off
	v_lshl_add_u64 v[114:115], v[114:115], 0, s[78:79]
	s_waitcnt lgkmcnt(3)
	v_mfma_f32_16x16x32_bf16 v[120:123], v[128:131], v[136:139], v[120:123]
	v_mfma_f32_16x16x32_bf16 v[124:127], v[128:131], v[144:147], v[124:127]
	s_waitcnt lgkmcnt(0)
	v_mfma_f32_16x16x32_bf16 v[120:123], v[132:135], v[140:143], v[120:123]
	v_mfma_f32_16x16x32_bf16 v[124:127], v[132:135], v[148:151], v[124:127]
	s_waitcnt vmcnt(9)
	s_barrier
	ds_read_b128 v[152:155], v97
	ds_read_b128 v[160:163], v102 offset:0
	ds_read_b128 v[168:171], v102 offset:2048
	ds_read_b128 v[156:159], v189
	ds_read_b128 v[164:167], v194 offset:0
	ds_read_b128 v[172:175], v194 offset:2048
	s_add_i32 m0, s76, 0
	s_nop 0
	global_load_lds_dwordx4 v[110:111], off
	v_lshl_add_u64 v[110:111], v[110:111], 0, s[78:79]
	s_add_i32 m0, s77, 0
	s_nop 0
	global_load_lds_dwordx4 v[112:113], off
	v_lshl_add_u64 v[112:113], v[112:113], 0, s[78:79]
	s_add_i32 m0, s77, 1024
	s_nop 0
	global_load_lds_dwordx4 v[114:115], off
	v_lshl_add_u64 v[114:115], v[114:115], 0, s[78:79]
	s_waitcnt lgkmcnt(3)
	v_mfma_f32_16x16x32_bf16 v[120:123], v[152:155], v[160:163], v[120:123]
	v_mfma_f32_16x16x32_bf16 v[124:127], v[152:155], v[168:171], v[124:127]
	s_waitcnt lgkmcnt(0)
	v_mfma_f32_16x16x32_bf16 v[120:123], v[156:159], v[164:167], v[120:123]
	v_mfma_f32_16x16x32_bf16 v[124:127], v[156:159], v[172:175], v[124:127]
	s_waitcnt vmcnt(9)
	s_barrier
	ds_read_b128 v[128:131], v98
	ds_read_b128 v[136:139], v103 offset:0
	ds_read_b128 v[144:147], v103 offset:2048
	ds_read_b128 v[132:135], v190
	ds_read_b128 v[140:143], v195 offset:0
	ds_read_b128 v[148:151], v195 offset:2048
	s_add_i32 m0, s76, 24576
	s_nop 0
	global_load_lds_dwordx4 v[110:111], off
	v_lshl_add_u64 v[110:111], v[110:111], 0, s[78:79]
	s_add_i32 m0, s77, 24576
	s_nop 0
	global_load_lds_dwordx4 v[112:113], off
	v_lshl_add_u64 v[112:113], v[112:113], 0, s[78:79]
	s_add_i32 m0, s77, 25600
	s_nop 0
	global_load_lds_dwordx4 v[114:115], off
	v_lshl_add_u64 v[114:115], v[114:115], 0, s[78:79]
	s_waitcnt lgkmcnt(3)
	v_mfma_f32_16x16x32_bf16 v[120:123], v[128:131], v[136:139], v[120:123]
	v_mfma_f32_16x16x32_bf16 v[124:127], v[128:131], v[144:147], v[124:127]
	s_waitcnt lgkmcnt(0)
	v_mfma_f32_16x16x32_bf16 v[120:123], v[132:135], v[140:143], v[120:123]
	v_mfma_f32_16x16x32_bf16 v[124:127], v[132:135], v[148:151], v[124:127]
	s_waitcnt vmcnt(9)
	s_barrier
; template <class F>
; __device__ __forceinline__ void small_gemm_ks(LAS unsigned char* lds, const bf16_t* A, int lda, const bf16_t* Bt, int ldb, int K, int N, int a_grp_cols, int bx, int G, int tid, const F& f) {
;     ...
;         for (int k0 = 0; k0 < KH; k0 += 32) { const bf16x8 av = *(const bf16x8*)(ap + k0);
; #pragma unroll
;             for (int nt = 0; nt < 2; ++nt) { const bf16x8 bv = *(const bf16x8*)(bp + (size_t)nt * 16 * ldb + k0); acc[nt] = __builtin_amdgcn_mfma_f32_16x16x32_bf16(av, bv, acc[nt], 0, 0, 0); } }
	ds_read_b128 v[152:155], v99
	ds_read_b128 v[160:163], v104 offset:0
	ds_read_b128 v[168:171], v104 offset:2048
	ds_read_b128 v[156:159], v191
	ds_read_b128 v[164:167], v196 offset:0
	ds_read_b128 v[172:175], v196 offset:2048
	s_add_i32 m0, s76, 49152
	s_nop 0
	global_load_lds_dwordx4 v[110:111], off
	v_lshl_add_u64 v[110:111], v[110:111], 0, s[78:79]
	s_add_i32 m0, s77, 49152
	s_nop 0
	global_load_lds_dwordx4 v[112:113], off
	v_lshl_add_u64 v[112:113], v[112:113], 0, s[78:79]
	s_add_i32 m0, s77, 50176
	s_nop 0
	global_load_lds_dwordx4 v[114:115], off
	v_lshl_add_u64 v[114:115], v[114:115], 0, s[78:79]
	s_waitcnt lgkmcnt(3)
	v_mfma_f32_16x16x32_bf16 v[120:123], v[152:155], v[160:163], v[120:123]
	v_mfma_f32_16x16x32_bf16 v[124:127], v[152:155], v[168:171], v[124:127]
	s_waitcnt lgkmcnt(0)
	v_mfma_f32_16x16x32_bf16 v[120:123], v[156:159], v[164:167], v[120:123]
	v_mfma_f32_16x16x32_bf16 v[124:127], v[156:159], v[172:175], v[124:127]
	s_waitcnt vmcnt(9)
	s_barrier
	ds_read_b128 v[128:131], v100
	ds_read_b128 v[136:139], v105 offset:0
	ds_read_b128 v[144:147], v105 offset:2048
	ds_read_b128 v[132:135], v192
	ds_read_b128 v[140:143], v197 offset:0
	ds_read_b128 v[148:151], v197 offset:2048
	s_add_i32 m0, s76, 73728
	s_nop 0
	global_load_lds_dwordx4 v[110:111], off
	v_lshl_add_u64 v[110:111], v[110:111], 0, s[78:79]
	s_add_i32 m0, s77, 73728
	s_nop 0
	global_load_lds_dwordx4 v[112:113], off
	v_lshl_add_u64 v[112:113], v[112:113], 0, s[78:79]
	s_add_i32 m0, s77, 74752
	s_nop 0
	global_load_lds_dwordx4 v[114:115], off
	v_lshl_add_u64 v[114:115], v[114:115], 0, s[78:79]
	s_waitcnt lgkmcnt(3)
	v_mfma_f32_16x16x32_bf16 v[120:123], v[128:131], v[136:139], v[120:123]
	v_mfma_f32_16x16x32_bf16 v[124:127], v[128:131], v[144:147], v[124:127]
	s_waitcnt lgkmcnt(0)
	v_mfma_f32_16x16x32_bf16 v[120:123], v[132:135], v[140:143], v[120:123]
	v_mfma_f32_16x16x32_bf16 v[124:127], v[132:135], v[148:151], v[124:127]
	s_waitcnt vmcnt(9)
	s_barrier
	ds_read_b128 v[152:155], v96
	ds_read_b128 v[160:163], v101 offset:0
	ds_read_b128 v[168:171], v101 offset:2048
	ds_read_b128 v[156:159], v188
	ds_read_b128 v[164:167], v193 offset:0
	ds_read_b128 v[172:175], v193 offset:2048
	s_add_i32 m0, s76, 98304
	s_nop 0
	global_load_lds_dwordx4 v[110:111], off
	v_lshl_add_u64 v[110:111], v[110:111], 0, s[78:79]
	s_add_i32 m0, s77, 98304
	s_nop 0
	global_load_lds_dwordx4 v[112:113], off
	v_lshl_add_u64 v[112:113], v[112:113], 0, s[78:79]
	s_add_i32 m0, s77, 99328
	s_nop 0
	global_load_lds_dwordx4 v[114:115], off
	v_lshl_add_u64 v[114:115], v[114:115], 0, s[78:79]
	s_waitcnt lgkmcnt(3)
	v_mfma_f32_16x16x32_bf16 v[120:123], v[152:155], v[160:163], v[120:123]
	v_mfma_f32_16x16x32_bf16 v[124:127], v[152:155], v[168:171], v[124:127]
	s_waitcnt lgkmcnt(0)
	v_mfma_f32_16x16x32_bf16 v[120:123], v[156:159], v[164:167], v[120:123]
	v_mfma_f32_16x16x32_bf16 v[124:127], v[156:159], v[172:175], v[124:127]
	s_waitcnt vmcnt(9)
	s_barrier
	ds_read_b128 v[128:131], v97
	ds_read_b128 v[136:139], v102 offset:0
	ds_read_b128 v[144:147], v102 offset:2048
	ds_read_b128 v[132:135], v189
	ds_read_b128 v[140:143], v194 offset:0
	ds_read_b128 v[148:151], v194 offset:2048
	s_add_i32 m0, s76, 0
	s_nop 0
	global_load_lds_dwordx4 v[110:111], off
	v_lshl_add_u64 v[110:111], v[110:111], 0, s[78:79]
	s_add_i32 m0, s77, 0
	s_nop 0
	global_load_lds_dwordx4 v[112:113], off
	v_lshl_add_u64 v[112:113], v[112:113], 0, s[78:79]
	s_add_i32 m0, s77, 1024
	s_nop 0
	global_load_lds_dwordx4 v[114:115], off
	v_lshl_add_u64 v[114:115], v[114:115], 0, s[78:79]
	s_waitcnt lgkmcnt(3)
	v_mfma_f32_16x16x32_bf16 v[120:123], v[128:131], v[136:139], v[120:123]
	v_mfma_f32_16x16x32_bf16 v[124:127], v[128:131], v[144:147], v[124:127]
	s_waitcnt lgkmcnt(0)
	v_mfma_f32_16x16x32_bf16 v[120:123], v[132:135], v[140:143], v[120:123]
	v_mfma_f32_16x16x32_bf16 v[124:127], v[132:135], v[148:151], v[124:127]
	s_waitcnt vmcnt(9)
	s_barrier
	ds_read_b128 v[152:155], v98
	ds_read_b128 v[160:163], v103 offset:0
	ds_read_b128 v[168:171], v103 offset:2048
	ds_read_b128 v[156:159], v190
	ds_read_b128 v[164:167], v195 offset:0
	ds_read_b128 v[172:175], v195 offset:2048
	s_add_i32 m0, s76, 24576
	s_nop 0
	global_load_lds_dwordx4 v[110:111], off
	v_lshl_add_u64 v[110:111], v[110:111], 0, s[78:79]
	s_add_i32 m0, s77, 24576
	s_nop 0
	global_load_lds_dwordx4 v[112:113], off
	v_lshl_add_u64 v[112:113], v[112:113], 0, s[78:79]
	s_add_i32 m0, s77, 25600
	s_nop 0
	global_load_lds_dwordx4 v[114:115], off
	v_lshl_add_u64 v[114:115], v[114:115], 0, s[78:79]
	s_waitcnt lgkmcnt(3)
	v_mfma_f32_16x16x32_bf16 v[120:123], v[152:155], v[160:163], v[120:123]
	v_mfma_f32_16x16x32_bf16 v[124:127], v[152:155], v[168:171], v[124:127]
	s_waitcnt lgkmcnt(0)
	v_mfma_f32_16x16x32_bf16 v[120:123], v[156:159], v[164:167], v[120:123]
	v_mfma_f32_16x16x32_bf16 v[124:127], v[156:159], v[172:175], v[124:127]
	s_waitcnt vmcnt(9)
	s_barrier
	ds_read_b128 v[128:131], v99
	ds_read_b128 v[136:139], v104 offset:0
	ds_read_b128 v[144:147], v104 offset:2048
	ds_read_b128 v[132:135], v191
	ds_read_b128 v[140:143], v196 offset:0
	ds_read_b128 v[148:151], v196 offset:2048
	s_add_i32 m0, s76, 49152
	s_nop 0
	global_load_lds_dwordx4 v[110:111], off
	v_lshl_add_u64 v[110:111], v[110:111], 0, s[78:79]
	s_add_i32 m0, s77, 49152
	s_nop 0
	global_load_lds_dwordx4 v[112:113], off
	v_lshl_add_u64 v[112:113], v[112:113], 0, s[78:79]
	s_add_i32 m0, s77, 50176
	s_nop 0
	global_load_lds_dwordx4 v[114:115], off
	v_lshl_add_u64 v[114:115], v[114:115], 0, s[78:79]
	s_waitcnt lgkmcnt(3)
	v_mfma_f32_16x16x32_bf16 v[120:123], v[128:131], v[136:139], v[120:123]
	v_mfma_f32_16x16x32_bf16 v[124:127], v[128:131], v[144:147], v[124:127]
	s_waitcnt lgkmcnt(0)
	v_mfma_f32_16x16x32_bf16 v[120:123], v[132:135], v[140:143], v[120:123]
	v_mfma_f32_16x16x32_bf16 v[124:127], v[132:135], v[148:151], v[124:127]
	s_waitcnt vmcnt(9)
	s_barrier
; template <class F>
; __device__ __forceinline__ void small_gemm_ks(LAS unsigned char* lds, const bf16_t* A, int lda, const bf16_t* Bt, int ldb, int K, int N, int a_grp_cols, int bx, int G, int tid, const F& f) {
;     ...
;         for (int k0 = 0; k0 < KH; k0 += 32) { const bf16x8 av = *(const bf16x8*)(ap + k0);
; #pragma unroll
;             for (int nt = 0; nt < 2; ++nt) { const bf16x8 bv = *(const bf16x8*)(bp + (size_t)nt * 16 * ldb + k0); acc[nt] = __builtin_amdgcn_mfma_f32_16x16x32_bf16(av, bv, acc[nt], 0, 0, 0); } }
	ds_read_b128 v[152:155], v100
	ds_read_b128 v[160:163], v105 offset:0
	ds_read_b128 v[168:171], v105 offset:2048
	ds_read_b128 v[156:159], v192
	ds_read_b128 v[164:167], v197 offset:0
	ds_read_b128 v[172:175], v197 offset:2048
	s_add_i32 m0, s76, 73728
	s_nop 0
	global_load_lds_dwordx4 v[110:111], off
	v_lshl_add_u64 v[110:111], v[110:111], 0, s[78:79]
	s_add_i32 m0, s77, 73728
	s_nop 0
	global_load_lds_dwordx4 v[112:113], off
	v_lshl_add_u64 v[112:113], v[112:113], 0, s[78:79]
	s_add_i32 m0, s77, 74752
	s_nop 0
	global_load_lds_dwordx4 v[114:115], off
	v_lshl_add_u64 v[114:115], v[114:115], 0, s[78:79]
	s_waitcnt lgkmcnt(3)
	v_mfma_f32_16x16x32_bf16 v[120:123], v[152:155], v[160:163], v[120:123]
	v_mfma_f32_16x16x32_bf16 v[124:127], v[152:155], v[168:171], v[124:127]
	s_waitcnt lgkmcnt(0)
	v_mfma_f32_16x16x32_bf16 v[120:123], v[156:159], v[164:167], v[120:123]
	v_mfma_f32_16x16x32_bf16 v[124:127], v[156:159], v[172:175], v[124:127]
	s_waitcnt vmcnt(9)
	s_barrier
	ds_read_b128 v[128:131], v96
	ds_read_b128 v[136:139], v101 offset:0
	ds_read_b128 v[144:147], v101 offset:2048
	ds_read_b128 v[132:135], v188
	ds_read_b128 v[140:143], v193 offset:0
	ds_read_b128 v[148:151], v193 offset:2048
	s_add_i32 m0, s76, 98304
	s_nop 0
	global_load_lds_dwordx4 v[110:111], off
	v_lshl_add_u64 v[110:111], v[110:111], 0, s[78:79]
	s_add_i32 m0, s77, 98304
	s_nop 0
	global_load_lds_dwordx4 v[112:113], off
	v_lshl_add_u64 v[112:113], v[112:113], 0, s[78:79]
	s_add_i32 m0, s77, 99328
	s_nop 0
	global_load_lds_dwordx4 v[114:115], off
	v_lshl_add_u64 v[114:115], v[114:115], 0, s[78:79]
	s_waitcnt lgkmcnt(3)
	v_mfma_f32_16x16x32_bf16 v[120:123], v[128:131], v[136:139], v[120:123]
	v_mfma_f32_16x16x32_bf16 v[124:127], v[128:131], v[144:147], v[124:127]
	s_waitcnt lgkmcnt(0)
	v_mfma_f32_16x16x32_bf16 v[120:123], v[132:135], v[140:143], v[120:123]
	v_mfma_f32_16x16x32_bf16 v[124:127], v[132:135], v[148:151], v[124:127]
	s_waitcnt vmcnt(9)
	s_barrier
	ds_read_b128 v[152:155], v97
	ds_read_b128 v[160:163], v102 offset:0
	ds_read_b128 v[168:171], v102 offset:2048
	ds_read_b128 v[156:159], v189
	ds_read_b128 v[164:167], v194 offset:0
	ds_read_b128 v[172:175], v194 offset:2048
	s_add_i32 m0, s76, 0
	s_nop 0
	global_load_lds_dwordx4 v[110:111], off
	v_lshl_add_u64 v[110:111], v[110:111], 0, s[78:79]
	s_add_i32 m0, s77, 0
	s_nop 0
	global_load_lds_dwordx4 v[112:113], off
	v_lshl_add_u64 v[112:113], v[112:113], 0, s[78:79]
	s_add_i32 m0, s77, 1024
	s_nop 0
	global_load_lds_dwordx4 v[114:115], off
	v_lshl_add_u64 v[114:115], v[114:115], 0, s[78:79]
	s_waitcnt lgkmcnt(3)
	v_mfma_f32_16x16x32_bf16 v[120:123], v[152:155], v[160:163], v[120:123]
	v_mfma_f32_16x16x32_bf16 v[124:127], v[152:155], v[168:171], v[124:127]
	s_waitcnt lgkmcnt(0)
	v_mfma_f32_16x16x32_bf16 v[120:123], v[156:159], v[164:167], v[120:123]
	v_mfma_f32_16x16x32_bf16 v[124:127], v[156:159], v[172:175], v[124:127]
	s_waitcnt vmcnt(9)
	s_barrier
	ds_read_b128 v[128:131], v98
	ds_read_b128 v[136:139], v103 offset:0
	ds_read_b128 v[144:147], v103 offset:2048
	ds_read_b128 v[132:135], v190
	ds_read_b128 v[140:143], v195 offset:0
	ds_read_b128 v[148:151], v195 offset:2048
	s_add_i32 m0, s76, 24576
	s_nop 0
	global_load_lds_dwordx4 v[110:111], off
	v_lshl_add_u64 v[110:111], v[110:111], 0, s[78:79]
	s_add_i32 m0, s77, 24576
	s_nop 0
	global_load_lds_dwordx4 v[112:113], off
	v_lshl_add_u64 v[112:113], v[112:113], 0, s[78:79]
	s_add_i32 m0, s77, 25600
	s_nop 0
	global_load_lds_dwordx4 v[114:115], off
	v_lshl_add_u64 v[114:115], v[114:115], 0, s[78:79]
	s_waitcnt lgkmcnt(3)
	v_mfma_f32_16x16x32_bf16 v[120:123], v[128:131], v[136:139], v[120:123]
	v_mfma_f32_16x16x32_bf16 v[124:127], v[128:131], v[144:147], v[124:127]
	s_waitcnt lgkmcnt(0)
	v_mfma_f32_16x16x32_bf16 v[120:123], v[132:135], v[140:143], v[120:123]
	v_mfma_f32_16x16x32_bf16 v[124:127], v[132:135], v[148:151], v[124:127]
	s_waitcnt vmcnt(9)
	s_barrier
	ds_read_b128 v[152:155], v99
	ds_read_b128 v[160:163], v104 offset:0
	ds_read_b128 v[168:171], v104 offset:2048
	ds_read_b128 v[156:159], v191
	ds_read_b128 v[164:167], v196 offset:0
	ds_read_b128 v[172:175], v196 offset:2048
	s_add_i32 m0, s76, 49152
	s_nop 0
	global_load_lds_dwordx4 v[110:111], off
	v_lshl_add_u64 v[110:111], v[110:111], 0, s[78:79]
	s_add_i32 m0, s77, 49152
	s_nop 0
	global_load_lds_dwordx4 v[112:113], off
	v_lshl_add_u64 v[112:113], v[112:113], 0, s[78:79]
	s_add_i32 m0, s77, 50176
	s_nop 0
	global_load_lds_dwordx4 v[114:115], off
	v_lshl_add_u64 v[114:115], v[114:115], 0, s[78:79]
	s_waitcnt lgkmcnt(3)
	v_mfma_f32_16x16x32_bf16 v[120:123], v[152:155], v[160:163], v[120:123]
	v_mfma_f32_16x16x32_bf16 v[124:127], v[152:155], v[168:171], v[124:127]
	s_waitcnt lgkmcnt(0)
	v_mfma_f32_16x16x32_bf16 v[120:123], v[156:159], v[164:167], v[120:123]
	v_mfma_f32_16x16x32_bf16 v[124:127], v[156:159], v[172:175], v[124:127]
	s_waitcnt vmcnt(9)
	s_barrier
	ds_read_b128 v[128:131], v100
	ds_read_b128 v[136:139], v105 offset:0
	ds_read_b128 v[144:147], v105 offset:2048
	ds_read_b128 v[132:135], v192
	ds_read_b128 v[140:143], v197 offset:0
	ds_read_b128 v[148:151], v197 offset:2048
	s_add_i32 m0, s76, 73728
	s_nop 0
	global_load_lds_dwordx4 v[110:111], off
	v_lshl_add_u64 v[110:111], v[110:111], 0, s[78:79]
	s_add_i32 m0, s77, 73728
	s_nop 0
	global_load_lds_dwordx4 v[112:113], off
	v_lshl_add_u64 v[112:113], v[112:113], 0, s[78:79]
	s_add_i32 m0, s77, 74752
	s_nop 0
	global_load_lds_dwordx4 v[114:115], off
	v_lshl_add_u64 v[114:115], v[114:115], 0, s[78:79]
	s_waitcnt lgkmcnt(3)
	v_mfma_f32_16x16x32_bf16 v[120:123], v[128:131], v[136:139], v[120:123]
	v_mfma_f32_16x16x32_bf16 v[124:127], v[128:131], v[144:147], v[124:127]
	s_waitcnt lgkmcnt(0)
	v_mfma_f32_16x16x32_bf16 v[120:123], v[132:135], v[140:143], v[120:123]
	v_mfma_f32_16x16x32_bf16 v[124:127], v[132:135], v[148:151], v[124:127]
	s_waitcnt vmcnt(9)
	s_barrier
; #define LAS __attribute__((address_space(3)))
; #define LDS_SYNC() do { asm volatile("s_waitcnt lgkmcnt(0)" ::: "memory"); __builtin_amdgcn_s_barrier(); asm volatile("" ::: "memory"); } while (0)
; template <class F>
; __device__ __forceinline__ void small_gemm_ks(LAS unsigned char* lds, const bf16_t* A, int lda, const bf16_t* Bt, int ldb, int K, int N, int a_grp_cols, int bx, int G, int tid, const F& f) {
;     ...
;         for (int k0 = 0; k0 < KH; k0 += 32) { const bf16x8 av = *(const bf16x8*)(ap + k0);
; #pragma unroll
;             for (int nt = 0; nt < 2; ++nt) { const bf16x8 bv = *(const bf16x8*)(bp + (size_t)nt * 16 * ldb + k0); acc[nt] = __builtin_amdgcn_mfma_f32_16x16x32_bf16(av, bv, acc[nt], 0, 0, 0); } }
;         if (kh == 1) { *(LAS f32x4*)(lds + ((wq * 2 + 0) * 64 + lane) * 16) = acc[0]; *(LAS f32x4*)(lds + ((wq * 2 + 1) * 64 + lane) * 16) = acc[1]; }
;         LDS_SYNC();
	ds_read_b128 v[152:155], v96
	ds_read_b128 v[160:163], v101 offset:0
	ds_read_b128 v[168:171], v101 offset:2048
	ds_read_b128 v[156:159], v188
	ds_read_b128 v[164:167], v193 offset:0
	ds_read_b128 v[172:175], v193 offset:2048
	s_add_i32 m0, s76, 98304
	s_nop 0
	global_load_lds_dwordx4 v[110:111], off
	v_lshl_add_u64 v[110:111], v[110:111], 0, s[78:79]
	s_add_i32 m0, s77, 98304
	s_nop 0
	global_load_lds_dwordx4 v[112:113], off
	v_lshl_add_u64 v[112:113], v[112:113], 0, s[78:79]
	s_add_i32 m0, s77, 99328
	s_nop 0
	global_load_lds_dwordx4 v[114:115], off
	v_lshl_add_u64 v[114:115], v[114:115], 0, s[78:79]
	s_waitcnt lgkmcnt(3)
	v_mfma_f32_16x16x32_bf16 v[120:123], v[152:155], v[160:163], v[120:123]
	v_mfma_f32_16x16x32_bf16 v[124:127], v[152:155], v[168:171], v[124:127]
	s_waitcnt lgkmcnt(0)
	v_mfma_f32_16x16x32_bf16 v[120:123], v[156:159], v[164:167], v[120:123]
	v_mfma_f32_16x16x32_bf16 v[124:127], v[156:159], v[172:175], v[124:127]
	s_waitcnt vmcnt(9)
	s_barrier
	ds_read_b128 v[128:131], v97
	ds_read_b128 v[136:139], v102 offset:0
	ds_read_b128 v[144:147], v102 offset:2048
	ds_read_b128 v[132:135], v189
	ds_read_b128 v[140:143], v194 offset:0
	ds_read_b128 v[148:151], v194 offset:2048
	s_add_i32 m0, s76, 0
	s_nop 0
	global_load_lds_dwordx4 v[110:111], off
	v_lshl_add_u64 v[110:111], v[110:111], 0, s[78:79]
	s_add_i32 m0, s77, 0
	s_nop 0
	global_load_lds_dwordx4 v[112:113], off
	v_lshl_add_u64 v[112:113], v[112:113], 0, s[78:79]
	s_add_i32 m0, s77, 1024
	s_nop 0
	global_load_lds_dwordx4 v[114:115], off
	v_lshl_add_u64 v[114:115], v[114:115], 0, s[78:79]
	s_waitcnt lgkmcnt(3)
	v_mfma_f32_16x16x32_bf16 v[120:123], v[128:131], v[136:139], v[120:123]
	v_mfma_f32_16x16x32_bf16 v[124:127], v[128:131], v[144:147], v[124:127]
	s_waitcnt lgkmcnt(0)
	v_mfma_f32_16x16x32_bf16 v[120:123], v[132:135], v[140:143], v[120:123]
	v_mfma_f32_16x16x32_bf16 v[124:127], v[132:135], v[148:151], v[124:127]
	s_waitcnt vmcnt(9)
	s_barrier
	ds_read_b128 v[152:155], v98
	ds_read_b128 v[160:163], v103 offset:0
	ds_read_b128 v[168:171], v103 offset:2048
	ds_read_b128 v[156:159], v190
	ds_read_b128 v[164:167], v195 offset:0
	ds_read_b128 v[172:175], v195 offset:2048
	s_add_i32 m0, s76, 24576
	s_nop 0
	global_load_lds_dwordx4 v[110:111], off
	v_lshl_add_u64 v[110:111], v[110:111], 0, s[78:79]
	s_add_i32 m0, s77, 24576
	s_nop 0
	global_load_lds_dwordx4 v[112:113], off
	v_lshl_add_u64 v[112:113], v[112:113], 0, s[78:79]
	s_add_i32 m0, s77, 25600
	s_nop 0
	global_load_lds_dwordx4 v[114:115], off
	v_lshl_add_u64 v[114:115], v[114:115], 0, s[78:79]
	s_waitcnt lgkmcnt(3)
	v_mfma_f32_16x16x32_bf16 v[120:123], v[152:155], v[160:163], v[120:123]
	v_mfma_f32_16x16x32_bf16 v[124:127], v[152:155], v[168:171], v[124:127]
	s_waitcnt lgkmcnt(0)
	v_mfma_f32_16x16x32_bf16 v[120:123], v[156:159], v[164:167], v[120:123]
	v_mfma_f32_16x16x32_bf16 v[124:127], v[156:159], v[172:175], v[124:127]
	s_waitcnt vmcnt(9)
	s_barrier
	ds_read_b128 v[128:131], v99
	ds_read_b128 v[136:139], v104 offset:0
	ds_read_b128 v[144:147], v104 offset:2048
	ds_read_b128 v[132:135], v191
	ds_read_b128 v[140:143], v196 offset:0
	ds_read_b128 v[148:151], v196 offset:2048
	s_waitcnt lgkmcnt(3)
	v_mfma_f32_16x16x32_bf16 v[120:123], v[128:131], v[136:139], v[120:123]
	v_mfma_f32_16x16x32_bf16 v[124:127], v[128:131], v[144:147], v[124:127]
	s_waitcnt lgkmcnt(0)
	v_mfma_f32_16x16x32_bf16 v[120:123], v[132:135], v[140:143], v[120:123]
	v_mfma_f32_16x16x32_bf16 v[124:127], v[132:135], v[148:151], v[124:127]
	s_waitcnt vmcnt(6)
	s_barrier
	ds_read_b128 v[152:155], v100
	ds_read_b128 v[160:163], v105 offset:0
	ds_read_b128 v[168:171], v105 offset:2048
	ds_read_b128 v[156:159], v192
	ds_read_b128 v[164:167], v197 offset:0
	ds_read_b128 v[172:175], v197 offset:2048
	s_waitcnt lgkmcnt(3)
	v_mfma_f32_16x16x32_bf16 v[120:123], v[152:155], v[160:163], v[120:123]
	v_mfma_f32_16x16x32_bf16 v[124:127], v[152:155], v[168:171], v[124:127]
	s_waitcnt lgkmcnt(0)
	v_mfma_f32_16x16x32_bf16 v[120:123], v[156:159], v[164:167], v[120:123]
	v_mfma_f32_16x16x32_bf16 v[124:127], v[156:159], v[172:175], v[124:127]
	s_waitcnt vmcnt(3)
	s_barrier
	ds_read_b128 v[128:131], v96
	ds_read_b128 v[136:139], v101 offset:0
	ds_read_b128 v[144:147], v101 offset:2048
	ds_read_b128 v[132:135], v188
	ds_read_b128 v[140:143], v193 offset:0
	ds_read_b128 v[148:151], v193 offset:2048
	s_waitcnt lgkmcnt(3)
	v_mfma_f32_16x16x32_bf16 v[120:123], v[128:131], v[136:139], v[120:123]
	v_mfma_f32_16x16x32_bf16 v[124:127], v[128:131], v[144:147], v[124:127]
	s_waitcnt lgkmcnt(0)
	v_mfma_f32_16x16x32_bf16 v[120:123], v[132:135], v[140:143], v[120:123]
	v_mfma_f32_16x16x32_bf16 v[124:127], v[132:135], v[148:151], v[124:127]
	s_waitcnt vmcnt(0)
	s_barrier
	ds_read_b128 v[152:155], v97
	ds_read_b128 v[160:163], v102 offset:0
	ds_read_b128 v[168:171], v102 offset:2048
	ds_read_b128 v[156:159], v189
	ds_read_b128 v[164:167], v194 offset:0
	ds_read_b128 v[172:175], v194 offset:2048
	s_waitcnt lgkmcnt(3)
	v_mfma_f32_16x16x32_bf16 v[120:123], v[152:155], v[160:163], v[120:123]
	v_mfma_f32_16x16x32_bf16 v[124:127], v[152:155], v[168:171], v[124:127]
	s_waitcnt lgkmcnt(0)
	v_mfma_f32_16x16x32_bf16 v[120:123], v[156:159], v[164:167], v[120:123]
	v_mfma_f32_16x16x32_bf16 v[124:127], v[156:159], v[172:175], v[124:127]
	s_barrier
	s_lshl_b32 s59, s82, 11
	s_lshl_b32 s62, s83, 1
	s_add_i32 s59, s59, s62
	s_add_u32 s60, s54, s59
	s_addc_u32 s61, s55, 0
	s_add_u32 s60, s60, 0x5700000
	s_addc_u32 s61, s61, 0
	v_lshl_add_u64 v[176:177], s[60:61], 0, v[106:107]
	s_mov_b32 s62, 0x1000
	s_mov_b32 s63, 0
	v_lshl_add_u64 v[178:179], v[176:177], 0, s[62:63]
	s_cmp_eq_u32 s70, 0
	s_cbranch_scc1 .Lsg_dn0_lo
	s_nop 4
	ds_write_b128 v109, v[120:123]
	ds_write_b128 v109, v[124:127] offset:1024
	s_waitcnt lgkmcnt(0)
	s_barrier
	s_branch .Lsg_dn0_done

; template <int WM, int WN, int NT, class F>
; __device__ __forceinline__ void small_gemm(const bf16_t* A, int lda, const bf16_t* Bt, int ldb, int K, int N, int a_grp_cols, int bx, int G, int tid, const F& f) {
;     ...
;     for (int t = bx; t < ntiles; t += G) {
;         const int row0 = MP + (t / ntn) * TM + wm * 16, n0 = (t % ntn) * TN + wn * 16 * NT;
;         const bf16_t* ap = A + (size_t)(row0 + c) * lda + (n0 >> 8) * a_grp_cols + 8 * g;
;         const bf16_t* bp = Bt + (size_t)(n0 + c) * ldb + 8 * g;
;         f32x4 acc[NT];
; #pragma unroll
;         for (int nt = 0; nt < NT; ++nt) acc[nt] = (f32x4){0.f, 0.f, 0.f, 0.f};
; #pragma unroll 8
;         for (int k0 = 0; k0 < K; k0 += 32) { const bf16x8 av = *(const bf16x8*)(ap + k0);
; #pragma unroll
;             for (int nt = 0; nt < NT; ++nt) { const bf16x8 bv = *(const bf16x8*)(bp + (size_t)nt * 16 * ldb + k0); acc[nt] = __builtin_amdgcn_mfma_f32_16x16x32_bf16(av, bv, acc[nt], 0, 0, 0); } }
.Lsg_hin_tile:
	s_lshr_b32 s1, s35, 5
	s_and_b32 s27, s35, 31
	s_lshl_b32 s1, s1, 6
	s_add_i32 s1, s1, 0x4000
	s_lshr_b32 s36, s27, 3
	s_lshl_b32 s33, s0, 3
	s_add_i32 s33, s33, s1
	s_lshl_b32 s33, s33, 11
	s_add_u32 s10, s6, s33
	s_addc_u32 s11, s7, 0
	s_add_u32 s10, s10, 0x7800000
	s_addc_u32 s11, s11, 0
	v_lshl_add_u64 v[6:7], s[10:11], 0, v[4:5]
	s_lshl_b32 s33, s27, 7
	s_lshl_b32 s34, s0, 4
	s_add_i32 s33, s33, s34
	s_lshl_b32 s33, s33, 11
	s_add_u32 s10, s6, s33
	s_addc_u32 s11, s7, 0
	s_add_u32 s10, s10, 0x2280000
	s_addc_u32 s11, s11, 0
	v_lshl_add_u64 v[8:9], s[10:11], 0, v[4:5]
	s_add_u32 s10, s10, 0x4000
	s_addc_u32 s11, s11, 0
	v_lshl_add_u64 v[10:11], s[10:11], 0, v[4:5]
	s_and_b32 s33, s35, 7
	s_lshl_b32 s34, s33, 9
	v_add_u32_e32 v1, s34, v86
	v_add_u32_e32 v2, 0x1000, v1
	global_load_dword v128, v1, s[16:17] offset:0
	global_load_dword v132, v2, s[16:17] offset:0
	global_load_dword v129, v1, s[16:17] offset:64
	global_load_dword v133, v2, s[16:17] offset:64
	global_load_dword v130, v1, s[16:17] offset:128
	global_load_dword v134, v2, s[16:17] offset:128
	global_load_dword v131, v1, s[16:17] offset:192
	global_load_dword v135, v2, s[16:17] offset:192
	v_mov_b32_e32 v24, 0
	v_mov_b32_e32 v25, 0
	v_mov_b32_e32 v26, 0
	v_mov_b32_e32 v27, 0
	v_mov_b32_e32 v28, 0
	v_mov_b32_e32 v29, 0
	v_mov_b32_e32 v30, 0
	v_mov_b32_e32 v31, 0
	v_mov_b32_e32 v36, 0
	v_mov_b32_e32 v37, 0
	v_mov_b32_e32 v38, 0
	v_mov_b32_e32 v39, 0
	v_mov_b32_e32 v40, 0
	v_mov_b32_e32 v41, 0
	v_mov_b32_e32 v42, 0
	v_mov_b32_e32 v43, 0
	s_add_i32 m0, s24, 0
	s_nop 0
	global_load_lds_dwordx4 v[6:7], off
	v_lshl_add_u64 v[6:7], v[6:7], 0, s[4:5]
	s_add_i32 m0, s25, 0
	s_nop 0
	global_load_lds_dwordx4 v[8:9], off
	v_lshl_add_u64 v[8:9], v[8:9], 0, s[4:5]
	s_add_i32 m0, s25, 1024
	s_nop 0
	global_load_lds_dwordx4 v[10:11], off
	v_lshl_add_u64 v[10:11], v[10:11], 0, s[4:5]
	s_add_i32 m0, s24, 24576
	s_nop 0
	global_load_lds_dwordx4 v[6:7], off
	v_lshl_add_u64 v[6:7], v[6:7], 0, s[4:5]
	s_add_i32 m0, s25, 24576
	s_nop 0
	global_load_lds_dwordx4 v[8:9], off
	v_lshl_add_u64 v[8:9], v[8:9], 0, s[4:5]
	s_add_i32 m0, s25, 25600
	s_nop 0
	global_load_lds_dwordx4 v[10:11], off
	v_lshl_add_u64 v[10:11], v[10:11], 0, s[4:5]
	s_add_i32 m0, s24, 49152
	s_nop 0
	global_load_lds_dwordx4 v[6:7], off
	v_lshl_add_u64 v[6:7], v[6:7], 0, s[4:5]
	s_add_i32 m0, s25, 49152
	s_nop 0
	global_load_lds_dwordx4 v[8:9], off
	v_lshl_add_u64 v[8:9], v[8:9], 0, s[4:5]
	s_add_i32 m0, s25, 50176
	s_nop 0
	global_load_lds_dwordx4 v[10:11], off
	v_lshl_add_u64 v[10:11], v[10:11], 0, s[4:5]
	s_add_i32 m0, s24, 73728
	s_nop 0
	global_load_lds_dwordx4 v[6:7], off
	v_lshl_add_u64 v[6:7], v[6:7], 0, s[4:5]
	s_add_i32 m0, s25, 73728
	s_nop 0
	global_load_lds_dwordx4 v[8:9], off
	v_lshl_add_u64 v[8:9], v[8:9], 0, s[4:5]
	s_add_i32 m0, s25, 74752
	s_nop 0
	global_load_lds_dwordx4 v[10:11], off
	v_lshl_add_u64 v[10:11], v[10:11], 0, s[4:5]
	s_waitcnt vmcnt(9)
	s_barrier
	ds_read_b128 v[44:47], v12
	ds_read_b128 v[52:55], v17 offset:0
	ds_read_b128 v[60:63], v17 offset:2048
	ds_read_b128 v[68:71], v17 offset:4096
	ds_read_b128 v[76:79], v17 offset:6144
	ds_read_b128 v[48:51], v144
	ds_read_b128 v[56:59], v149 offset:0
	ds_read_b128 v[64:67], v149 offset:2048
	ds_read_b128 v[72:75], v149 offset:4096
	ds_read_b128 v[80:83], v149 offset:6144
	s_add_i32 m0, s24, 98304
	s_nop 0
	global_load_lds_dwordx4 v[6:7], off
	v_lshl_add_u64 v[6:7], v[6:7], 0, s[4:5]
	s_add_i32 m0, s25, 98304
	s_nop 0
	global_load_lds_dwordx4 v[8:9], off
	v_lshl_add_u64 v[8:9], v[8:9], 0, s[4:5]
	s_add_i32 m0, s25, 99328
	s_nop 0
	global_load_lds_dwordx4 v[10:11], off
	v_lshl_add_u64 v[10:11], v[10:11], 0, s[4:5]
	s_waitcnt lgkmcnt(5)
	v_mfma_f32_16x16x32_bf16 v[24:27], v[44:47], v[52:55], v[24:27]
	v_mfma_f32_16x16x32_bf16 v[28:31], v[44:47], v[60:63], v[28:31]
	v_mfma_f32_16x16x32_bf16 v[36:39], v[44:47], v[68:71], v[36:39]
	v_mfma_f32_16x16x32_bf16 v[40:43], v[44:47], v[76:79], v[40:43]
	s_waitcnt lgkmcnt(0)
	v_mfma_f32_16x16x32_bf16 v[24:27], v[48:51], v[56:59], v[24:27]
	v_mfma_f32_16x16x32_bf16 v[28:31], v[48:51], v[64:67], v[28:31]
	v_mfma_f32_16x16x32_bf16 v[36:39], v[48:51], v[72:75], v[36:39]
	v_mfma_f32_16x16x32_bf16 v[40:43], v[48:51], v[80:83], v[40:43]
	s_waitcnt vmcnt(9)
	s_barrier
	ds_read_b128 v[88:91], v13
	ds_read_b128 v[96:99], v18 offset:0
	ds_read_b128 v[104:107], v18 offset:2048
	ds_read_b128 v[112:115], v18 offset:4096
	ds_read_b128 v[120:123], v18 offset:6144
	ds_read_b128 v[92:95], v145
	ds_read_b128 v[100:103], v150 offset:0
	ds_read_b128 v[108:111], v150 offset:2048
	ds_read_b128 v[116:119], v150 offset:4096
	ds_read_b128 v[124:127], v150 offset:6144
	s_add_i32 m0, s24, 0
	s_nop 0
	global_load_lds_dwordx4 v[6:7], off
	v_lshl_add_u64 v[6:7], v[6:7], 0, s[4:5]
	s_add_i32 m0, s25, 0
	s_nop 0
	global_load_lds_dwordx4 v[8:9], off
	v_lshl_add_u64 v[8:9], v[8:9], 0, s[4:5]
	s_add_i32 m0, s25, 1024
	s_nop 0
	global_load_lds_dwordx4 v[10:11], off
	v_lshl_add_u64 v[10:11], v[10:11], 0, s[4:5]
	s_waitcnt lgkmcnt(5)
	v_mfma_f32_16x16x32_bf16 v[24:27], v[88:91], v[96:99], v[24:27]
	v_mfma_f32_16x16x32_bf16 v[28:31], v[88:91], v[104:107], v[28:31]
	v_mfma_f32_16x16x32_bf16 v[36:39], v[88:91], v[112:115], v[36:39]
	v_mfma_f32_16x16x32_bf16 v[40:43], v[88:91], v[120:123], v[40:43]
	s_waitcnt lgkmcnt(0)
	v_mfma_f32_16x16x32_bf16 v[24:27], v[92:95], v[100:103], v[24:27]
	v_mfma_f32_16x16x32_bf16 v[28:31], v[92:95], v[108:111], v[28:31]
	v_mfma_f32_16x16x32_bf16 v[36:39], v[92:95], v[116:119], v[36:39]
	v_mfma_f32_16x16x32_bf16 v[40:43], v[92:95], v[124:127], v[40:43]
	s_waitcnt vmcnt(9)
	s_barrier
; template <int WM, int WN, int NT, class F>
; __device__ __forceinline__ void small_gemm(const bf16_t* A, int lda, const bf16_t* Bt, int ldb, int K, int N, int a_grp_cols, int bx, int G, int tid, const F& f) {
;     ...
;         for (int k0 = 0; k0 < K; k0 += 32) { const bf16x8 av = *(const bf16x8*)(ap + k0);
; #pragma unroll
;             for (int nt = 0; nt < NT; ++nt) { const bf16x8 bv = *(const bf16x8*)(bp + (size_t)nt * 16 * ldb + k0); acc[nt] = __builtin_amdgcn_mfma_f32_16x16x32_bf16(av, bv, acc[nt], 0, 0, 0); } }
	ds_read_b128 v[44:47], v14
	ds_read_b128 v[52:55], v19 offset:0
	ds_read_b128 v[60:63], v19 offset:2048
	ds_read_b128 v[68:71], v19 offset:4096
	ds_read_b128 v[76:79], v19 offset:6144
	ds_read_b128 v[48:51], v146
	ds_read_b128 v[56:59], v151 offset:0
	ds_read_b128 v[64:67], v151 offset:2048
	ds_read_b128 v[72:75], v151 offset:4096
	ds_read_b128 v[80:83], v151 offset:6144
	s_add_i32 m0, s24, 24576
	s_nop 0
	global_load_lds_dwordx4 v[6:7], off
	v_lshl_add_u64 v[6:7], v[6:7], 0, s[4:5]
	s_add_i32 m0, s25, 24576
	s_nop 0
	global_load_lds_dwordx4 v[8:9], off
	v_lshl_add_u64 v[8:9], v[8:9], 0, s[4:5]
	s_add_i32 m0, s25, 25600
	s_nop 0
	global_load_lds_dwordx4 v[10:11], off
	v_lshl_add_u64 v[10:11], v[10:11], 0, s[4:5]
	s_waitcnt lgkmcnt(5)
	v_mfma_f32_16x16x32_bf16 v[24:27], v[44:47], v[52:55], v[24:27]
	v_mfma_f32_16x16x32_bf16 v[28:31], v[44:47], v[60:63], v[28:31]
	v_mfma_f32_16x16x32_bf16 v[36:39], v[44:47], v[68:71], v[36:39]
	v_mfma_f32_16x16x32_bf16 v[40:43], v[44:47], v[76:79], v[40:43]
	s_waitcnt lgkmcnt(0)
	v_mfma_f32_16x16x32_bf16 v[24:27], v[48:51], v[56:59], v[24:27]
	v_mfma_f32_16x16x32_bf16 v[28:31], v[48:51], v[64:67], v[28:31]
	v_mfma_f32_16x16x32_bf16 v[36:39], v[48:51], v[72:75], v[36:39]
	v_mfma_f32_16x16x32_bf16 v[40:43], v[48:51], v[80:83], v[40:43]
	s_waitcnt vmcnt(9)
	s_barrier
	ds_read_b128 v[88:91], v15
	ds_read_b128 v[96:99], v20 offset:0
	ds_read_b128 v[104:107], v20 offset:2048
	ds_read_b128 v[112:115], v20 offset:4096
	ds_read_b128 v[120:123], v20 offset:6144
	ds_read_b128 v[92:95], v147
	ds_read_b128 v[100:103], v152 offset:0
	ds_read_b128 v[108:111], v152 offset:2048
	ds_read_b128 v[116:119], v152 offset:4096
	ds_read_b128 v[124:127], v152 offset:6144
	s_add_i32 m0, s24, 49152
	s_nop 0
	global_load_lds_dwordx4 v[6:7], off
	v_lshl_add_u64 v[6:7], v[6:7], 0, s[4:5]
	s_add_i32 m0, s25, 49152
	s_nop 0
	global_load_lds_dwordx4 v[8:9], off
	v_lshl_add_u64 v[8:9], v[8:9], 0, s[4:5]
	s_add_i32 m0, s25, 50176
	s_nop 0
	global_load_lds_dwordx4 v[10:11], off
	v_lshl_add_u64 v[10:11], v[10:11], 0, s[4:5]
	s_waitcnt lgkmcnt(5)
	v_mfma_f32_16x16x32_bf16 v[24:27], v[88:91], v[96:99], v[24:27]
	v_mfma_f32_16x16x32_bf16 v[28:31], v[88:91], v[104:107], v[28:31]
	v_mfma_f32_16x16x32_bf16 v[36:39], v[88:91], v[112:115], v[36:39]
	v_mfma_f32_16x16x32_bf16 v[40:43], v[88:91], v[120:123], v[40:43]
	s_waitcnt lgkmcnt(0)
	v_mfma_f32_16x16x32_bf16 v[24:27], v[92:95], v[100:103], v[24:27]
	v_mfma_f32_16x16x32_bf16 v[28:31], v[92:95], v[108:111], v[28:31]
	v_mfma_f32_16x16x32_bf16 v[36:39], v[92:95], v[116:119], v[36:39]
	v_mfma_f32_16x16x32_bf16 v[40:43], v[92:95], v[124:127], v[40:43]
	s_waitcnt vmcnt(9)
	s_barrier
	ds_read_b128 v[44:47], v16
	ds_read_b128 v[52:55], v21 offset:0
	ds_read_b128 v[60:63], v21 offset:2048
	ds_read_b128 v[68:71], v21 offset:4096
	ds_read_b128 v[76:79], v21 offset:6144
	ds_read_b128 v[48:51], v148
	ds_read_b128 v[56:59], v153 offset:0
	ds_read_b128 v[64:67], v153 offset:2048
	ds_read_b128 v[72:75], v153 offset:4096
	ds_read_b128 v[80:83], v153 offset:6144
	s_add_i32 m0, s24, 73728
	s_nop 0
	global_load_lds_dwordx4 v[6:7], off
	v_lshl_add_u64 v[6:7], v[6:7], 0, s[4:5]
	s_add_i32 m0, s25, 73728
	s_nop 0
	global_load_lds_dwordx4 v[8:9], off
	v_lshl_add_u64 v[8:9], v[8:9], 0, s[4:5]
	s_add_i32 m0, s25, 74752
	s_nop 0
	global_load_lds_dwordx4 v[10:11], off
	v_lshl_add_u64 v[10:11], v[10:11], 0, s[4:5]
	s_waitcnt lgkmcnt(5)
	v_mfma_f32_16x16x32_bf16 v[24:27], v[44:47], v[52:55], v[24:27]
	v_mfma_f32_16x16x32_bf16 v[28:31], v[44:47], v[60:63], v[28:31]
	v_mfma_f32_16x16x32_bf16 v[36:39], v[44:47], v[68:71], v[36:39]
	v_mfma_f32_16x16x32_bf16 v[40:43], v[44:47], v[76:79], v[40:43]
	s_waitcnt lgkmcnt(0)
	v_mfma_f32_16x16x32_bf16 v[24:27], v[48:51], v[56:59], v[24:27]
	v_mfma_f32_16x16x32_bf16 v[28:31], v[48:51], v[64:67], v[28:31]
	v_mfma_f32_16x16x32_bf16 v[36:39], v[48:51], v[72:75], v[36:39]
	v_mfma_f32_16x16x32_bf16 v[40:43], v[48:51], v[80:83], v[40:43]
	s_waitcnt vmcnt(9)
	s_barrier
	ds_read_b128 v[88:91], v12
	ds_read_b128 v[96:99], v17 offset:0
	ds_read_b128 v[104:107], v17 offset:2048
	ds_read_b128 v[112:115], v17 offset:4096
	ds_read_b128 v[120:123], v17 offset:6144
	ds_read_b128 v[92:95], v144
	ds_read_b128 v[100:103], v149 offset:0
	ds_read_b128 v[108:111], v149 offset:2048
	ds_read_b128 v[116:119], v149 offset:4096
	ds_read_b128 v[124:127], v149 offset:6144
	s_add_i32 m0, s24, 98304
	s_nop 0
	global_load_lds_dwordx4 v[6:7], off
	v_lshl_add_u64 v[6:7], v[6:7], 0, s[4:5]
	s_add_i32 m0, s25, 98304
	s_nop 0
	global_load_lds_dwordx4 v[8:9], off
	v_lshl_add_u64 v[8:9], v[8:9], 0, s[4:5]
	s_add_i32 m0, s25, 99328
	s_nop 0
	global_load_lds_dwordx4 v[10:11], off
	v_lshl_add_u64 v[10:11], v[10:11], 0, s[4:5]
	s_waitcnt lgkmcnt(5)
	v_mfma_f32_16x16x32_bf16 v[24:27], v[88:91], v[96:99], v[24:27]
	v_mfma_f32_16x16x32_bf16 v[28:31], v[88:91], v[104:107], v[28:31]
	v_mfma_f32_16x16x32_bf16 v[36:39], v[88:91], v[112:115], v[36:39]
	v_mfma_f32_16x16x32_bf16 v[40:43], v[88:91], v[120:123], v[40:43]
	s_waitcnt lgkmcnt(0)
	v_mfma_f32_16x16x32_bf16 v[24:27], v[92:95], v[100:103], v[24:27]
	v_mfma_f32_16x16x32_bf16 v[28:31], v[92:95], v[108:111], v[28:31]
	v_mfma_f32_16x16x32_bf16 v[36:39], v[92:95], v[116:119], v[36:39]
	v_mfma_f32_16x16x32_bf16 v[40:43], v[92:95], v[124:127], v[40:43]
	s_waitcnt vmcnt(9)
	s_barrier
; template <int WM, int WN, int NT, class F>
; __device__ __forceinline__ void small_gemm(const bf16_t* A, int lda, const bf16_t* Bt, int ldb, int K, int N, int a_grp_cols, int bx, int G, int tid, const F& f) {
;     ...
;         for (int k0 = 0; k0 < K; k0 += 32) { const bf16x8 av = *(const bf16x8*)(ap + k0);
; #pragma unroll
;             for (int nt = 0; nt < NT; ++nt) { const bf16x8 bv = *(const bf16x8*)(bp + (size_t)nt * 16 * ldb + k0); acc[nt] = __builtin_amdgcn_mfma_f32_16x16x32_bf16(av, bv, acc[nt], 0, 0, 0); } }
	ds_read_b128 v[44:47], v13
	ds_read_b128 v[52:55], v18 offset:0
	ds_read_b128 v[60:63], v18 offset:2048
	ds_read_b128 v[68:71], v18 offset:4096
	ds_read_b128 v[76:79], v18 offset:6144
	ds_read_b128 v[48:51], v145
	ds_read_b128 v[56:59], v150 offset:0
	ds_read_b128 v[64:67], v150 offset:2048
	ds_read_b128 v[72:75], v150 offset:4096
	ds_read_b128 v[80:83], v150 offset:6144
	s_add_i32 m0, s24, 0
	s_nop 0
	global_load_lds_dwordx4 v[6:7], off
	v_lshl_add_u64 v[6:7], v[6:7], 0, s[4:5]
	s_add_i32 m0, s25, 0
	s_nop 0
	global_load_lds_dwordx4 v[8:9], off
	v_lshl_add_u64 v[8:9], v[8:9], 0, s[4:5]
	s_add_i32 m0, s25, 1024
	s_nop 0
	global_load_lds_dwordx4 v[10:11], off
	v_lshl_add_u64 v[10:11], v[10:11], 0, s[4:5]
	s_waitcnt lgkmcnt(5)
	v_mfma_f32_16x16x32_bf16 v[24:27], v[44:47], v[52:55], v[24:27]
	v_mfma_f32_16x16x32_bf16 v[28:31], v[44:47], v[60:63], v[28:31]
	v_mfma_f32_16x16x32_bf16 v[36:39], v[44:47], v[68:71], v[36:39]
	v_mfma_f32_16x16x32_bf16 v[40:43], v[44:47], v[76:79], v[40:43]
	s_waitcnt lgkmcnt(0)
	v_mfma_f32_16x16x32_bf16 v[24:27], v[48:51], v[56:59], v[24:27]
	v_mfma_f32_16x16x32_bf16 v[28:31], v[48:51], v[64:67], v[28:31]
	v_mfma_f32_16x16x32_bf16 v[36:39], v[48:51], v[72:75], v[36:39]
	v_mfma_f32_16x16x32_bf16 v[40:43], v[48:51], v[80:83], v[40:43]
	s_waitcnt vmcnt(9)
	s_barrier
	ds_read_b128 v[88:91], v14
	ds_read_b128 v[96:99], v19 offset:0
	ds_read_b128 v[104:107], v19 offset:2048
	ds_read_b128 v[112:115], v19 offset:4096
	ds_read_b128 v[120:123], v19 offset:6144
	ds_read_b128 v[92:95], v146
	ds_read_b128 v[100:103], v151 offset:0
	ds_read_b128 v[108:111], v151 offset:2048
	ds_read_b128 v[116:119], v151 offset:4096
	ds_read_b128 v[124:127], v151 offset:6144
	s_add_i32 m0, s24, 24576
	s_nop 0
	global_load_lds_dwordx4 v[6:7], off
	v_lshl_add_u64 v[6:7], v[6:7], 0, s[4:5]
	s_add_i32 m0, s25, 24576
	s_nop 0
	global_load_lds_dwordx4 v[8:9], off
	v_lshl_add_u64 v[8:9], v[8:9], 0, s[4:5]
	s_add_i32 m0, s25, 25600
	s_nop 0
	global_load_lds_dwordx4 v[10:11], off
	v_lshl_add_u64 v[10:11], v[10:11], 0, s[4:5]
	s_waitcnt lgkmcnt(5)
	v_mfma_f32_16x16x32_bf16 v[24:27], v[88:91], v[96:99], v[24:27]
	v_mfma_f32_16x16x32_bf16 v[28:31], v[88:91], v[104:107], v[28:31]
	v_mfma_f32_16x16x32_bf16 v[36:39], v[88:91], v[112:115], v[36:39]
	v_mfma_f32_16x16x32_bf16 v[40:43], v[88:91], v[120:123], v[40:43]
	s_waitcnt lgkmcnt(0)
	v_mfma_f32_16x16x32_bf16 v[24:27], v[92:95], v[100:103], v[24:27]
	v_mfma_f32_16x16x32_bf16 v[28:31], v[92:95], v[108:111], v[28:31]
	v_mfma_f32_16x16x32_bf16 v[36:39], v[92:95], v[116:119], v[36:39]
	v_mfma_f32_16x16x32_bf16 v[40:43], v[92:95], v[124:127], v[40:43]
	s_waitcnt vmcnt(9)
	s_barrier
	ds_read_b128 v[44:47], v15
	ds_read_b128 v[52:55], v20 offset:0
	ds_read_b128 v[60:63], v20 offset:2048
	ds_read_b128 v[68:71], v20 offset:4096
	ds_read_b128 v[76:79], v20 offset:6144
	ds_read_b128 v[48:51], v147
	ds_read_b128 v[56:59], v152 offset:0
	ds_read_b128 v[64:67], v152 offset:2048
	ds_read_b128 v[72:75], v152 offset:4096
	ds_read_b128 v[80:83], v152 offset:6144
	s_add_i32 m0, s24, 49152
	s_nop 0
	global_load_lds_dwordx4 v[6:7], off
	v_lshl_add_u64 v[6:7], v[6:7], 0, s[4:5]
	s_add_i32 m0, s25, 49152
	s_nop 0
	global_load_lds_dwordx4 v[8:9], off
	v_lshl_add_u64 v[8:9], v[8:9], 0, s[4:5]
	s_add_i32 m0, s25, 50176
	s_nop 0
	global_load_lds_dwordx4 v[10:11], off
	v_lshl_add_u64 v[10:11], v[10:11], 0, s[4:5]
	s_waitcnt lgkmcnt(5)
	v_mfma_f32_16x16x32_bf16 v[24:27], v[44:47], v[52:55], v[24:27]
	v_mfma_f32_16x16x32_bf16 v[28:31], v[44:47], v[60:63], v[28:31]
	v_mfma_f32_16x16x32_bf16 v[36:39], v[44:47], v[68:71], v[36:39]
	v_mfma_f32_16x16x32_bf16 v[40:43], v[44:47], v[76:79], v[40:43]
	s_waitcnt lgkmcnt(0)
	v_mfma_f32_16x16x32_bf16 v[24:27], v[48:51], v[56:59], v[24:27]
	v_mfma_f32_16x16x32_bf16 v[28:31], v[48:51], v[64:67], v[28:31]
	v_mfma_f32_16x16x32_bf16 v[36:39], v[48:51], v[72:75], v[36:39]
	v_mfma_f32_16x16x32_bf16 v[40:43], v[48:51], v[80:83], v[40:43]
	s_waitcnt vmcnt(9)
	s_barrier
	ds_read_b128 v[88:91], v16
	ds_read_b128 v[96:99], v21 offset:0
	ds_read_b128 v[104:107], v21 offset:2048
	ds_read_b128 v[112:115], v21 offset:4096
	ds_read_b128 v[120:123], v21 offset:6144
	ds_read_b128 v[92:95], v148
	ds_read_b128 v[100:103], v153 offset:0
	ds_read_b128 v[108:111], v153 offset:2048
	ds_read_b128 v[116:119], v153 offset:4096
	ds_read_b128 v[124:127], v153 offset:6144
	s_add_i32 m0, s24, 73728
	s_nop 0
	global_load_lds_dwordx4 v[6:7], off
	v_lshl_add_u64 v[6:7], v[6:7], 0, s[4:5]
	s_add_i32 m0, s25, 73728
	s_nop 0
	global_load_lds_dwordx4 v[8:9], off
	v_lshl_add_u64 v[8:9], v[8:9], 0, s[4:5]
	s_add_i32 m0, s25, 74752
	s_nop 0
	global_load_lds_dwordx4 v[10:11], off
	v_lshl_add_u64 v[10:11], v[10:11], 0, s[4:5]
	s_waitcnt lgkmcnt(5)
	v_mfma_f32_16x16x32_bf16 v[24:27], v[88:91], v[96:99], v[24:27]
	v_mfma_f32_16x16x32_bf16 v[28:31], v[88:91], v[104:107], v[28:31]
	v_mfma_f32_16x16x32_bf16 v[36:39], v[88:91], v[112:115], v[36:39]
	v_mfma_f32_16x16x32_bf16 v[40:43], v[88:91], v[120:123], v[40:43]
	s_waitcnt lgkmcnt(0)
	v_mfma_f32_16x16x32_bf16 v[24:27], v[92:95], v[100:103], v[24:27]
	v_mfma_f32_16x16x32_bf16 v[28:31], v[92:95], v[108:111], v[28:31]
	v_mfma_f32_16x16x32_bf16 v[36:39], v[92:95], v[116:119], v[36:39]
	v_mfma_f32_16x16x32_bf16 v[40:43], v[92:95], v[124:127], v[40:43]
	s_waitcnt vmcnt(9)
	s_barrier
; template <int WM, int WN, int NT, class F>
; __device__ __forceinline__ void small_gemm(const bf16_t* A, int lda, const bf16_t* Bt, int ldb, int K, int N, int a_grp_cols, int bx, int G, int tid, const F& f) {
;     ...
;         for (int k0 = 0; k0 < K; k0 += 32) { const bf16x8 av = *(const bf16x8*)(ap + k0);
; #pragma unroll
;             for (int nt = 0; nt < NT; ++nt) { const bf16x8 bv = *(const bf16x8*)(bp + (size_t)nt * 16 * ldb + k0); acc[nt] = __builtin_amdgcn_mfma_f32_16x16x32_bf16(av, bv, acc[nt], 0, 0, 0); } }
	ds_read_b128 v[44:47], v12
	ds_read_b128 v[52:55], v17 offset:0
	ds_read_b128 v[60:63], v17 offset:2048
	ds_read_b128 v[68:71], v17 offset:4096
	ds_read_b128 v[76:79], v17 offset:6144
	ds_read_b128 v[48:51], v144
	ds_read_b128 v[56:59], v149 offset:0
	ds_read_b128 v[64:67], v149 offset:2048
	ds_read_b128 v[72:75], v149 offset:4096
	ds_read_b128 v[80:83], v149 offset:6144
	s_add_i32 m0, s24, 98304
	s_nop 0
	global_load_lds_dwordx4 v[6:7], off
	v_lshl_add_u64 v[6:7], v[6:7], 0, s[4:5]
	s_add_i32 m0, s25, 98304
	s_nop 0
	global_load_lds_dwordx4 v[8:9], off
	v_lshl_add_u64 v[8:9], v[8:9], 0, s[4:5]
	s_add_i32 m0, s25, 99328
	s_nop 0
	global_load_lds_dwordx4 v[10:11], off
	v_lshl_add_u64 v[10:11], v[10:11], 0, s[4:5]
	s_waitcnt lgkmcnt(5)
	v_mfma_f32_16x16x32_bf16 v[24:27], v[44:47], v[52:55], v[24:27]
	v_mfma_f32_16x16x32_bf16 v[28:31], v[44:47], v[60:63], v[28:31]
	v_mfma_f32_16x16x32_bf16 v[36:39], v[44:47], v[68:71], v[36:39]
	v_mfma_f32_16x16x32_bf16 v[40:43], v[44:47], v[76:79], v[40:43]
	s_waitcnt lgkmcnt(0)
	v_mfma_f32_16x16x32_bf16 v[24:27], v[48:51], v[56:59], v[24:27]
	v_mfma_f32_16x16x32_bf16 v[28:31], v[48:51], v[64:67], v[28:31]
	v_mfma_f32_16x16x32_bf16 v[36:39], v[48:51], v[72:75], v[36:39]
	v_mfma_f32_16x16x32_bf16 v[40:43], v[48:51], v[80:83], v[40:43]
	s_waitcnt vmcnt(9)
	s_barrier
	ds_read_b128 v[88:91], v13
	ds_read_b128 v[96:99], v18 offset:0
	ds_read_b128 v[104:107], v18 offset:2048
	ds_read_b128 v[112:115], v18 offset:4096
	ds_read_b128 v[120:123], v18 offset:6144
	ds_read_b128 v[92:95], v145
	ds_read_b128 v[100:103], v150 offset:0
	ds_read_b128 v[108:111], v150 offset:2048
	ds_read_b128 v[116:119], v150 offset:4096
	ds_read_b128 v[124:127], v150 offset:6144
	s_add_i32 m0, s24, 0
	s_nop 0
	global_load_lds_dwordx4 v[6:7], off
	v_lshl_add_u64 v[6:7], v[6:7], 0, s[4:5]
	s_add_i32 m0, s25, 0
	s_nop 0
	global_load_lds_dwordx4 v[8:9], off
	v_lshl_add_u64 v[8:9], v[8:9], 0, s[4:5]
	s_add_i32 m0, s25, 1024
	s_nop 0
	global_load_lds_dwordx4 v[10:11], off
	v_lshl_add_u64 v[10:11], v[10:11], 0, s[4:5]
	s_waitcnt lgkmcnt(5)
	v_mfma_f32_16x16x32_bf16 v[24:27], v[88:91], v[96:99], v[24:27]
	v_mfma_f32_16x16x32_bf16 v[28:31], v[88:91], v[104:107], v[28:31]
	v_mfma_f32_16x16x32_bf16 v[36:39], v[88:91], v[112:115], v[36:39]
	v_mfma_f32_16x16x32_bf16 v[40:43], v[88:91], v[120:123], v[40:43]
	s_waitcnt lgkmcnt(0)
	v_mfma_f32_16x16x32_bf16 v[24:27], v[92:95], v[100:103], v[24:27]
	v_mfma_f32_16x16x32_bf16 v[28:31], v[92:95], v[108:111], v[28:31]
	v_mfma_f32_16x16x32_bf16 v[36:39], v[92:95], v[116:119], v[36:39]
	v_mfma_f32_16x16x32_bf16 v[40:43], v[92:95], v[124:127], v[40:43]
	s_waitcnt vmcnt(9)
	s_barrier
	ds_read_b128 v[44:47], v14
	ds_read_b128 v[52:55], v19 offset:0
	ds_read_b128 v[60:63], v19 offset:2048
	ds_read_b128 v[68:71], v19 offset:4096
	ds_read_b128 v[76:79], v19 offset:6144
	ds_read_b128 v[48:51], v146
	ds_read_b128 v[56:59], v151 offset:0
	ds_read_b128 v[64:67], v151 offset:2048
	ds_read_b128 v[72:75], v151 offset:4096
	ds_read_b128 v[80:83], v151 offset:6144
	s_waitcnt lgkmcnt(5)
	v_mfma_f32_16x16x32_bf16 v[24:27], v[44:47], v[52:55], v[24:27]
	v_mfma_f32_16x16x32_bf16 v[28:31], v[44:47], v[60:63], v[28:31]
	v_mfma_f32_16x16x32_bf16 v[36:39], v[44:47], v[68:71], v[36:39]
	v_mfma_f32_16x16x32_bf16 v[40:43], v[44:47], v[76:79], v[40:43]
	s_waitcnt lgkmcnt(0)
	v_mfma_f32_16x16x32_bf16 v[24:27], v[48:51], v[56:59], v[24:27]
	v_mfma_f32_16x16x32_bf16 v[28:31], v[48:51], v[64:67], v[28:31]
	v_mfma_f32_16x16x32_bf16 v[36:39], v[48:51], v[72:75], v[36:39]
	v_mfma_f32_16x16x32_bf16 v[40:43], v[48:51], v[80:83], v[40:43]
	s_waitcnt vmcnt(6)
	s_barrier
	ds_read_b128 v[88:91], v15
	ds_read_b128 v[96:99], v20 offset:0
	ds_read_b128 v[104:107], v20 offset:2048
	ds_read_b128 v[112:115], v20 offset:4096
	ds_read_b128 v[120:123], v20 offset:6144
	ds_read_b128 v[92:95], v147
	ds_read_b128 v[100:103], v152 offset:0
	ds_read_b128 v[108:111], v152 offset:2048
	ds_read_b128 v[116:119], v152 offset:4096
	ds_read_b128 v[124:127], v152 offset:6144
	s_waitcnt lgkmcnt(5)
	v_mfma_f32_16x16x32_bf16 v[24:27], v[88:91], v[96:99], v[24:27]
	v_mfma_f32_16x16x32_bf16 v[28:31], v[88:91], v[104:107], v[28:31]
	v_mfma_f32_16x16x32_bf16 v[36:39], v[88:91], v[112:115], v[36:39]
	v_mfma_f32_16x16x32_bf16 v[40:43], v[88:91], v[120:123], v[40:43]
	s_waitcnt lgkmcnt(0)
	v_mfma_f32_16x16x32_bf16 v[24:27], v[92:95], v[100:103], v[24:27]
	v_mfma_f32_16x16x32_bf16 v[28:31], v[92:95], v[108:111], v[28:31]
	v_mfma_f32_16x16x32_bf16 v[36:39], v[92:95], v[116:119], v[36:39]
	v_mfma_f32_16x16x32_bf16 v[40:43], v[92:95], v[124:127], v[40:43]
	s_waitcnt vmcnt(3)
	s_barrier
	ds_read_b128 v[44:47], v16
	ds_read_b128 v[52:55], v21 offset:0
	ds_read_b128 v[60:63], v21 offset:2048
	ds_read_b128 v[68:71], v21 offset:4096
	ds_read_b128 v[76:79], v21 offset:6144
	ds_read_b128 v[48:51], v148
	ds_read_b128 v[56:59], v153 offset:0
	ds_read_b128 v[64:67], v153 offset:2048
	ds_read_b128 v[72:75], v153 offset:4096
	ds_read_b128 v[80:83], v153 offset:6144
	s_waitcnt lgkmcnt(5)
	v_mfma_f32_16x16x32_bf16 v[24:27], v[44:47], v[52:55], v[24:27]
	v_mfma_f32_16x16x32_bf16 v[28:31], v[44:47], v[60:63], v[28:31]
	v_mfma_f32_16x16x32_bf16 v[36:39], v[44:47], v[68:71], v[36:39]
	v_mfma_f32_16x16x32_bf16 v[40:43], v[44:47], v[76:79], v[40:43]
	s_waitcnt lgkmcnt(0)
	v_mfma_f32_16x16x32_bf16 v[24:27], v[48:51], v[56:59], v[24:27]
	v_mfma_f32_16x16x32_bf16 v[28:31], v[48:51], v[64:67], v[28:31]
	v_mfma_f32_16x16x32_bf16 v[36:39], v[48:51], v[72:75], v[36:39]
	v_mfma_f32_16x16x32_bf16 v[40:43], v[48:51], v[80:83], v[40:43]
	s_waitcnt vmcnt(0)
	s_barrier
	ds_read_b128 v[88:91], v12
	ds_read_b128 v[96:99], v17 offset:0
	ds_read_b128 v[104:107], v17 offset:2048
	ds_read_b128 v[112:115], v17 offset:4096
	ds_read_b128 v[120:123], v17 offset:6144
	ds_read_b128 v[92:95], v144
	ds_read_b128 v[100:103], v149 offset:0
	ds_read_b128 v[108:111], v149 offset:2048
	ds_read_b128 v[116:119], v149 offset:4096
	ds_read_b128 v[124:127], v149 offset:6144
	s_waitcnt lgkmcnt(5)
	v_mfma_f32_16x16x32_bf16 v[24:27], v[88:91], v[96:99], v[24:27]
	v_mfma_f32_16x16x32_bf16 v[28:31], v[88:91], v[104:107], v[28:31]
	v_mfma_f32_16x16x32_bf16 v[36:39], v[88:91], v[112:115], v[36:39]
	v_mfma_f32_16x16x32_bf16 v[40:43], v[88:91], v[120:123], v[40:43]
	s_waitcnt lgkmcnt(0)
	v_mfma_f32_16x16x32_bf16 v[24:27], v[92:95], v[100:103], v[24:27]
	v_mfma_f32_16x16x32_bf16 v[28:31], v[92:95], v[108:111], v[28:31]
	v_mfma_f32_16x16x32_bf16 v[36:39], v[92:95], v[116:119], v[36:39]
	v_mfma_f32_16x16x32_bf16 v[40:43], v[92:95], v[124:127], v[40:43]
	s_barrier
	s_add_u32 s28, s6, 0xdb00000
	s_addc_u32 s29, s7, 0
	s_cmp_eq_u32 s36, 0
	s_cselect_b32 s28, s18, s28
	s_cselect_b32 s29, s19, s29
	s_cmp_eq_u32 s36, 1
	s_cselect_b32 s28, s20, s28
	s_cselect_b32 s29, s21, s29
	s_cmp_eq_u32 s36, 3
	s_cselect_b32 s28, s22, s28
	s_cselect_b32 s29, s23, s29
	s_lshl_b32 s33, s1, 11
	s_and_b32 s34, s35, 7
	s_lshl_b32 s34, s34, 8
	s_add_i32 s33, s33, s34
	s_add_u32 s28, s28, s33
	s_addc_u32 s29, s29, 0
	v_lshl_add_u64 v[136:137], s[28:29], 0, v[34:35]
	s_mov_b32 s30, 0x1000
	s_mov_b32 s31, 0
	v_lshl_add_u64 v[138:139], v[136:137], 0, s[30:31]
	s_cmp_eq_u32 s36, 2
	s_cbranch_scc1 .Lsg_hin_st
	s_cmp_eq_u32 s36, 1
	s_cbranch_scc1 .Lsg_hin_k
	v_mul_f32_e32 v140, 0xbfb8aa3b, v24
	v_mul_f32_e32 v141, 0xbfb8aa3b, v25
	v_mul_f32_e32 v142, 0xbfb8aa3b, v26
	v_mul_f32_e32 v143, 0xbfb8aa3b, v27
	v_exp_f32_e32 v140, v140
	v_exp_f32_e32 v141, v141
	v_exp_f32_e32 v142, v142
	v_exp_f32_e32 v143, v143
	v_add_f32_e32 v140, 1.0, v140
	v_add_f32_e32 v141, 1.0, v141
	v_add_f32_e32 v142, 1.0, v142
	v_add_f32_e32 v143, 1.0, v143
	v_rcp_f32_e32 v140, v140
	v_rcp_f32_e32 v141, v141
	v_rcp_f32_e32 v142, v142
	v_rcp_f32_e32 v143, v143
	v_mul_f32_e32 v24, v24, v140
	v_mul_f32_e32 v25, v25, v141
	v_mul_f32_e32 v26, v26, v142
	v_mul_f32_e32 v27, v27, v143
	v_mul_f32_e32 v140, 0xbfb8aa3b, v28
	v_mul_f32_e32 v141, 0xbfb8aa3b, v29
	v_mul_f32_e32 v142, 0xbfb8aa3b, v30
	v_mul_f32_e32 v143, 0xbfb8aa3b, v31
	v_exp_f32_e32 v140, v140
	v_exp_f32_e32 v141, v141
	v_exp_f32_e32 v142, v142
	v_exp_f32_e32 v143, v143
	v_add_f32_e32 v140, 1.0, v140
	v_add_f32_e32 v141, 1.0, v141
	v_add_f32_e32 v142, 1.0, v142
	v_add_f32_e32 v143, 1.0, v143
	v_rcp_f32_e32 v140, v140
	v_rcp_f32_e32 v141, v141
	v_rcp_f32_e32 v142, v142
	v_rcp_f32_e32 v143, v143
	v_mul_f32_e32 v28, v28, v140
	v_mul_f32_e32 v29, v29, v141
	v_mul_f32_e32 v30, v30, v142
	v_mul_f32_e32 v31, v31, v143
	v_mul_f32_e32 v140, 0xbfb8aa3b, v36
	v_mul_f32_e32 v141, 0xbfb8aa3b, v37
	v_mul_f32_e32 v142, 0xbfb8aa3b, v38
	v_mul_f32_e32 v143, 0xbfb8aa3b, v39
	v_exp_f32_e32 v140, v140
	v_exp_f32_e32 v141, v141
	v_exp_f32_e32 v142, v142
	v_exp_f32_e32 v143, v143
	v_add_f32_e32 v140, 1.0, v140
	v_add_f32_e32 v141, 1.0, v141
	v_add_f32_e32 v142, 1.0, v142
	v_add_f32_e32 v143, 1.0, v143
	v_rcp_f32_e32 v140, v140
	v_rcp_f32_e32 v141, v141
	v_rcp_f32_e32 v142, v142
	v_rcp_f32_e32 v143, v143
	v_mul_f32_e32 v36, v36, v140
	v_mul_f32_e32 v37, v37, v141
	v_mul_f32_e32 v38, v38, v142
	v_mul_f32_e32 v39, v39, v143
	v_mul_f32_e32 v140, 0xbfb8aa3b, v40
	v_mul_f32_e32 v141, 0xbfb8aa3b, v41
	v_mul_f32_e32 v142, 0xbfb8aa3b, v42
	v_mul_f32_e32 v143, 0xbfb8aa3b, v43
	v_exp_f32_e32 v140, v140
	v_exp_f32_e32 v141, v141
	v_exp_f32_e32 v142, v142
	v_exp_f32_e32 v143, v143
	v_add_f32_e32 v140, 1.0, v140
	v_add_f32_e32 v141, 1.0, v141
	v_add_f32_e32 v142, 1.0, v142
	v_add_f32_e32 v143, 1.0, v143
	v_rcp_f32_e32 v140, v140
	v_rcp_f32_e32 v141, v141
	v_rcp_f32_e32 v142, v142
	v_rcp_f32_e32 v143, v143
	v_mul_f32_e32 v40, v40, v140
	v_mul_f32_e32 v41, v41, v141
	v_mul_f32_e32 v42, v42, v142
	v_mul_f32_e32 v43, v43, v143
	s_cmp_eq_u32 s36, 0
	s_cbranch_scc0 .Lsg_hin_st
	v_mul_f32_e32 v24, 0x3db504f3, v24
	v_mul_f32_e32 v25, 0x3db504f3, v25
	v_mul_f32_e32 v26, 0x3db504f3, v26
	v_mul_f32_e32 v27, 0x3db504f3, v27
	v_mul_f32_e32 v28, 0x3db504f3, v28
	v_mul_f32_e32 v29, 0x3db504f3, v29
	v_mul_f32_e32 v30, 0x3db504f3, v30
	v_mul_f32_e32 v31, 0x3db504f3, v31
	v_mul_f32_e32 v36, 0x3db504f3, v36
	v_mul_f32_e32 v37, 0x3db504f3, v37
	v_mul_f32_e32 v38, 0x3db504f3, v38
	v_mul_f32_e32 v39, 0x3db504f3, v39
	v_mul_f32_e32 v40, 0x3db504f3, v40
	v_mul_f32_e32 v41, 0x3db504f3, v41
	v_mul_f32_e32 v42, 0x3db504f3, v42
	v_mul_f32_e32 v43, 0x3db504f3, v43
	s_branch .Lsg_hin_st

; __device__ __forceinline__ unsigned f2bf(float f) { unsigned u = __builtin_bit_cast(unsigned, f); return (u + 0x7fffu + ((u >> 16) & 1u)) >> 16; }
.Lsg_hin_st:
	s_nop 7
	v_bfe_u32 v140, v24, 16, 1
	v_bfe_u32 v141, v25, 16, 1
	v_bfe_u32 v142, v26, 16, 1
	v_bfe_u32 v143, v27, 16, 1
	v_add3_u32 v140, v24, v140, s3
	v_add3_u32 v141, v25, v141, s3
	v_add3_u32 v142, v26, v142, s3
	v_add3_u32 v143, v27, v143, s3
	global_store_short_d16_hi v[136:137], v140, off offset:0
	global_store_short_d16_hi v[136:137], v141, off offset:2048
	global_store_short_d16_hi v[138:139], v142, off offset:0
	global_store_short_d16_hi v[138:139], v143, off offset:2048
	v_bfe_u32 v140, v28, 16, 1
	v_bfe_u32 v141, v29, 16, 1
	v_bfe_u32 v142, v30, 16, 1
	v_bfe_u32 v143, v31, 16, 1
	v_add3_u32 v140, v28, v140, s3
	v_add3_u32 v141, v29, v141, s3
	v_add3_u32 v142, v30, v142, s3
	v_add3_u32 v143, v31, v143, s3
	global_store_short_d16_hi v[136:137], v140, off offset:32
	global_store_short_d16_hi v[136:137], v141, off offset:2080
	global_store_short_d16_hi v[138:139], v142, off offset:32
	global_store_short_d16_hi v[138:139], v143, off offset:2080
	v_bfe_u32 v140, v36, 16, 1
	v_bfe_u32 v141, v37, 16, 1
	v_bfe_u32 v142, v38, 16, 1
	v_bfe_u32 v143, v39, 16, 1
	v_add3_u32 v140, v36, v140, s3
	v_add3_u32 v141, v37, v141, s3
	v_add3_u32 v142, v38, v142, s3
	v_add3_u32 v143, v39, v143, s3
	global_store_short_d16_hi v[136:137], v140, off offset:64
	global_store_short_d16_hi v[136:137], v141, off offset:2112
	global_store_short_d16_hi v[138:139], v142, off offset:64
	global_store_short_d16_hi v[138:139], v143, off offset:2112
	v_bfe_u32 v140, v40, 16, 1
	v_bfe_u32 v141, v41, 16, 1
	v_bfe_u32 v142, v42, 16, 1
	v_bfe_u32 v143, v43, 16, 1
	v_add3_u32 v140, v40, v140, s3
	v_add3_u32 v141, v41, v141, s3
	v_add3_u32 v142, v42, v142, s3
	v_add3_u32 v143, v43, v143, s3
	global_store_short_d16_hi v[136:137], v140, off offset:96
	global_store_short_d16_hi v[136:137], v141, off offset:2144
	global_store_short_d16_hi v[138:139], v142, off offset:96
	global_store_short_d16_hi v[138:139], v143, off offset:2144
	s_waitcnt vmcnt(0)
	s_add_i32 s35, s35, s56
	s_cmpk_lt_i32 s35, 0x100
	s_cbranch_scc1 .Lsg_hin_tile

; #define LAS __attribute__((address_space(3)))
; __device__ __forceinline__ unsigned pk2(float lo, float hi) { const f32x2 v = {lo, hi}; const bf16x2_t b = __builtin_convertvector(v, bf16x2_t); return __builtin_bit_cast(unsigned, b); }
; #define LDS_SYNC() do { asm volatile("s_waitcnt lgkmcnt(0)" ::: "memory"); __builtin_amdgcn_s_barrier(); asm volatile("" ::: "memory"); } while (0)
; template <bool FULL> ...
;     ...
;                   u32x2 ov; ov.x = pk2(p[0], p[1]); ov.y = pk2(p[2], p[3]);
;                   *(LAS u32x2*)(lds + GL_PT + (16 * ti + c) * 144 + (16 * si + 4 * g) * 2) = ov; } }
;             LDS_SYNC();
;             bf16x8 SA[4];
; #pragma unroll
;             for (int kd = 0; kd < 4; ++kd) { u32x4 v; v.x = pk2(S[2 * kd][0], S[2 * kd][1]); v.y = pk2(S[2 * kd][2], S[2 * kd][3]); v.z = pk2(S[2 * kd + 1][0], S[2 * kd + 1][1]); v.w = pk2(S[2 * kd + 1][2], S[2 * kd + 1][3]);
;                 SA[kd] = __builtin_bit_cast(bf16x8, v); }
; #pragma unroll
;             for (int ti = 0; ti < 4; ++ti) { f32x4 acc = (f32x4){0.f, 0.f, 0.f, 0.f};
; #pragma unroll
;                 for (int ks = 0; ks < 2; ++ks) if (32 * ks <= 16 * ti + 15) { const bf16x8 A = *(const LAS bf16x8*)(lds + GL_VT + (16 * w + c) * 144 + (32 * ks + 8 * g) * 2);
;                     const bf16x8 B = *(const LAS bf16x8*)(lds + GL_PT + (16 * ti + c) * 144 + (32 * ks + 8 * g) * 2);
;                     acc = __builtin_amdgcn_mfma_f32_16x16x32_bf16(A, B, acc, 0, 0, 0); }
; #pragma unroll
;                 for (int kd = 0; kd < 4; ++kd) { const u32x2 b0 = *(const LAS u32x2*)(lds + GL_QO + (16 * ti + c) * 272 + (32 * kd + 4 * g) * 2), b1 = *(const LAS u32x2*)(lds + GL_QO + (16 * ti + c) * 272 + (32 * kd + 16 + 4 * g) * 2);
;                     acc = __builtin_amdgcn_mfma_f32_16x16x32_bf16(SA[kd], mk8(b0, b1), acc, 0, 0, 0); }
;                 o[ti] = acc; }
.LBB0_1429:
	v_cvt_pk_bf16_f32 v36, v36, v37
	v_cvt_pk_bf16_f32 v37, v38, v39
	ds_write_b64 v156, v[36:37]
	s_waitcnt lgkmcnt(0)
	s_barrier
	v_add_u32_e32 v230, 0x1000, v130
	v_add_u32_e32 v231, 0x2000, v130
	v_add_u32_e32 v189, 0x3000, v130
	v_add_u32_e32 v232, v123, v80
	v_add_u32_e32 v188, v124, v80
	v_add_u32_e32 v233, s33, v80
	ds_read_b128 v[52:55], v157
	ds_read_b128 v[56:59], v157 offset:64
	ds_read_b128 v[176:179], v129
	ds_read2_b64 v[184:187], v130 offset0:0 offset1:4
	ds_read2_b64 v[190:193], v130 offset0:8 offset1:12
	ds_read2_b64 v[194:197], v130 offset0:16 offset1:20
	ds_read2_b64 v[198:201], v130 offset0:24 offset1:28
	ds_read_b128 v[202:205], v232
	ds_read2_b64 v[214:217], v230 offset0:32 offset1:36
	ds_read2_b64 v[218:221], v230 offset0:40 offset1:44
	ds_read2_b64 v[222:225], v230 offset0:48 offset1:52
	ds_read2_b64 v[226:229], v230 offset0:56 offset1:60
	v_cvt_pk_bf16_f32 v68, v28, v29
	v_cvt_pk_bf16_f32 v69, v30, v31
	v_cvt_pk_bf16_f32 v70, v24, v25
	v_cvt_pk_bf16_f32 v71, v26, v27
	v_cvt_pk_bf16_f32 v64, v20, v21
	v_cvt_pk_bf16_f32 v65, v22, v23
	v_cvt_pk_bf16_f32 v66, v16, v17
	v_cvt_pk_bf16_f32 v67, v18, v19
	v_cvt_pk_bf16_f32 v60, v12, v13
	v_cvt_pk_bf16_f32 v61, v14, v15
	v_cvt_pk_bf16_f32 v62, v0, v1
	v_cvt_pk_bf16_f32 v63, v2, v3
	v_cvt_pk_bf16_f32 v172, v4, v5
	v_cvt_pk_bf16_f32 v173, v6, v7
	v_cvt_pk_bf16_f32 v174, v8, v9
	v_cvt_pk_bf16_f32 v175, v10, v11
	s_waitcnt lgkmcnt(11)
	s_waitcnt lgkmcnt(9)
	v_mfma_f32_16x16x32_bf16 v[48:51], v[52:55], v[176:179], 0
	s_waitcnt lgkmcnt(8)
	v_mfma_f32_16x16x32_bf16 v[48:51], v[68:71], v[184:187], v[48:51]
	s_waitcnt lgkmcnt(7)
	v_mfma_f32_16x16x32_bf16 v[48:51], v[64:67], v[190:193], v[48:51]
	s_waitcnt lgkmcnt(6)
	v_mfma_f32_16x16x32_bf16 v[48:51], v[60:63], v[194:197], v[48:51]
	s_waitcnt lgkmcnt(5)
	v_mfma_f32_16x16x32_bf16 v[48:51], v[172:175], v[198:201], v[48:51]
	ds_read_b128 v[176:179], v131
	ds_read_b128 v[180:183], v131 offset:64
	ds_read2_b64 v[184:187], v231 offset0:64 offset1:68
	ds_read2_b64 v[190:193], v231 offset0:72 offset1:76
	ds_read2_b64 v[194:197], v231 offset0:80 offset1:84
	ds_read2_b64 v[198:201], v231 offset0:88 offset1:92
	s_waitcnt lgkmcnt(10)
	v_mfma_f32_16x16x32_bf16 v[44:47], v[52:55], v[202:205], 0
	s_waitcnt lgkmcnt(9)
	v_mfma_f32_16x16x32_bf16 v[44:47], v[68:71], v[214:217], v[44:47]
	s_waitcnt lgkmcnt(8)
	v_mfma_f32_16x16x32_bf16 v[44:47], v[64:67], v[218:221], v[44:47]
	s_waitcnt lgkmcnt(7)
	v_mfma_f32_16x16x32_bf16 v[44:47], v[60:63], v[222:225], v[44:47]
	s_waitcnt lgkmcnt(6)
	v_mfma_f32_16x16x32_bf16 v[44:47], v[172:175], v[226:229], v[44:47]
	ds_read_b128 v[202:205], v132
	ds_read_b128 v[210:213], v132 offset:64
	ds_read2_b64 v[214:217], v189 offset0:96 offset1:100
	ds_read2_b64 v[218:221], v189 offset0:104 offset1:108
	ds_read2_b64 v[222:225], v189 offset0:112 offset1:116
	ds_read2_b64 v[226:229], v189 offset0:120 offset1:124
	s_waitcnt lgkmcnt(11)
	v_mfma_f32_16x16x32_bf16 v[40:43], v[52:55], v[176:179], 0
	s_waitcnt lgkmcnt(10)
	v_mfma_f32_16x16x32_bf16 v[40:43], v[56:59], v[180:183], v[40:43]
	s_waitcnt lgkmcnt(9)
	v_mfma_f32_16x16x32_bf16 v[40:43], v[68:71], v[184:187], v[40:43]
	s_waitcnt lgkmcnt(8)
	v_mfma_f32_16x16x32_bf16 v[40:43], v[64:67], v[190:193], v[40:43]
	s_waitcnt lgkmcnt(7)
	v_mfma_f32_16x16x32_bf16 v[40:43], v[60:63], v[194:197], v[40:43]
	s_waitcnt lgkmcnt(6)
	v_mfma_f32_16x16x32_bf16 v[40:43], v[172:175], v[198:201], v[40:43]
	ds_read_b128 v[176:179], v233
	ds_read_b128 v[180:183], v188 offset:52224
	ds_read_b128 v[184:187], v188 offset:52288
	ds_read_b128 v[190:193], v137
	ds_read_b128 v[194:197], v133 offset:52224
	ds_read_b128 v[198:201], v133 offset:52288
	s_waitcnt lgkmcnt(11)
	v_mfma_f32_16x16x32_bf16 v[36:39], v[52:55], v[202:205], 0
	s_waitcnt lgkmcnt(10)
	v_mfma_f32_16x16x32_bf16 v[36:39], v[56:59], v[210:213], v[36:39]
	s_waitcnt lgkmcnt(9)
; #define LAS __attribute__((address_space(3)))
; template <bool FULL> ...
;     ...
;         for (int dt = 0; dt < 8; ++dt) { const f32x4 dec = *(const LAS f32x4*)(lds + GL_DEC + (16 * dt + 4 * g) * 4); f32x4 acc = S[dt] * dec;
; #pragma unroll
;             for (int ks = 0; ks < 2; ++ks) { const bf16x8 A = *(const LAS bf16x8*)(lds + GL_KT + (16 * dt + c) * 144 + (32 * ks + 8 * g) * 2);
;                 const bf16x8 B = *(const LAS bf16x8*)(lds + GL_VT + (16 * w + c) * 144 + (32 * ks + 8 * g) * 2);
;                 acc = __builtin_amdgcn_mfma_f32_16x16x32_bf16(A, B, acc, 0, 0, 0); }
;             S[dt] = acc; }
;         if (FULL) {
; #pragma unroll
;             for (int ti = 0; ti < 4; ++ti) { float q = (o[ti][0] * o[ti][0] + o[ti][1] * o[ti][1]) + (o[ti][2] * o[ti][2] + o[ti][3] * o[ti][3]); q += __shfl_xor(q, 16); q += __shfl_xor(q, 32);
;                 if (g == 0) SS[w * 64 + 16 * ti + c] = q; }
	v_mfma_f32_16x16x32_bf16 v[36:39], v[68:71], v[214:217], v[36:39]
	s_waitcnt lgkmcnt(8)
	v_mfma_f32_16x16x32_bf16 v[36:39], v[64:67], v[218:221], v[36:39]
	s_waitcnt lgkmcnt(7)
	v_mfma_f32_16x16x32_bf16 v[36:39], v[60:63], v[222:225], v[36:39]
	s_waitcnt lgkmcnt(6)
	v_mfma_f32_16x16x32_bf16 v[36:39], v[172:175], v[226:229], v[36:39]
	ds_read_b128 v[202:205], v138
	ds_read_b128 v[210:213], v133 offset:54528
	ds_read_b128 v[214:217], v133 offset:54592
	ds_read_b128 v[218:221], v139
	ds_read_b128 v[222:225], v133 offset:56832
	ds_read_b128 v[226:229], v133 offset:56896
	s_waitcnt lgkmcnt(11)
	v_pk_mul_f32 v[28:29], v[28:29], v[176:177]
	v_pk_mul_f32 v[30:31], v[30:31], v[178:179]
	s_waitcnt lgkmcnt(8)
	v_pk_mul_f32 v[24:25], v[24:25], v[190:191]
	v_pk_mul_f32 v[26:27], v[26:27], v[192:193]
	v_mfma_f32_16x16x32_bf16 v[28:31], v[180:183], v[52:55], v[28:31]
	v_mfma_f32_16x16x32_bf16 v[28:31], v[184:187], v[56:59], v[28:31]
	s_waitcnt lgkmcnt(7)
	v_mfma_f32_16x16x32_bf16 v[24:27], v[194:197], v[52:55], v[24:27]
	s_waitcnt lgkmcnt(6)
	v_mfma_f32_16x16x32_bf16 v[24:27], v[198:201], v[56:59], v[24:27]
	ds_read_b128 v[176:179], v140
	ds_read_b128 v[180:183], v188 offset:61440
	ds_read_b128 v[184:187], v188 offset:61504
	ds_read_b128 v[190:193], v141
	ds_read_b128 v[194:197], v188 offset:63744
	ds_read_b128 v[198:201], v188 offset:63808
	s_waitcnt lgkmcnt(11)
	v_pk_mul_f32 v[20:21], v[20:21], v[202:203]
	v_pk_mul_f32 v[22:23], v[22:23], v[204:205]
	s_waitcnt lgkmcnt(8)
	v_pk_mul_f32 v[16:17], v[16:17], v[218:219]
	v_pk_mul_f32 v[18:19], v[18:19], v[220:221]
	v_mfma_f32_16x16x32_bf16 v[20:23], v[210:213], v[52:55], v[20:23]
	v_mfma_f32_16x16x32_bf16 v[20:23], v[214:217], v[56:59], v[20:23]
	s_waitcnt lgkmcnt(7)
	v_mfma_f32_16x16x32_bf16 v[16:19], v[222:225], v[52:55], v[16:19]
	s_waitcnt lgkmcnt(6)
	v_mfma_f32_16x16x32_bf16 v[16:19], v[226:229], v[56:59], v[16:19]
	ds_read_b128 v[202:205], v142
	ds_read_b128 v[210:213], v134 offset:13824
	ds_read_b128 v[214:217], v134 offset:13888
	ds_read_b128 v[218:221], v143
	ds_read_b128 v[222:225], v134 offset:16128
	ds_read_b128 v[226:229], v134 offset:16192
	s_waitcnt lgkmcnt(11)
	v_pk_mul_f32 v[12:13], v[12:13], v[176:177]
	v_pk_mul_f32 v[14:15], v[14:15], v[178:179]
	s_waitcnt lgkmcnt(8)
	v_pk_mul_f32 v[0:1], v[0:1], v[190:191]
	v_pk_mul_f32 v[2:3], v[2:3], v[192:193]
	v_mfma_f32_16x16x32_bf16 v[12:15], v[180:183], v[52:55], v[12:15]
	v_mfma_f32_16x16x32_bf16 v[12:15], v[184:187], v[56:59], v[12:15]
	s_waitcnt lgkmcnt(7)
	v_mfma_f32_16x16x32_bf16 v[0:3], v[194:197], v[52:55], v[0:3]
	s_waitcnt lgkmcnt(6)
	v_mfma_f32_16x16x32_bf16 v[0:3], v[198:201], v[56:59], v[0:3]
	s_waitcnt lgkmcnt(5)
	v_pk_mul_f32 v[4:5], v[4:5], v[202:203]
	v_pk_mul_f32 v[6:7], v[6:7], v[204:205]
	s_waitcnt lgkmcnt(2)
	v_pk_mul_f32 v[8:9], v[8:9], v[218:219]
	v_pk_mul_f32 v[10:11], v[10:11], v[220:221]
	v_mfma_f32_16x16x32_bf16 v[4:7], v[210:213], v[52:55], v[4:7]
	v_mfma_f32_16x16x32_bf16 v[4:7], v[214:217], v[56:59], v[4:7]
	s_waitcnt lgkmcnt(1)
	v_mfma_f32_16x16x32_bf16 v[8:11], v[222:225], v[52:55], v[8:11]
	s_waitcnt lgkmcnt(0)
	v_mfma_f32_16x16x32_bf16 v[8:11], v[226:229], v[56:59], v[8:11]
	v_and_b32_e32 v53, 64, v144
	v_xor_b32_e32 v52, 16, v144
	v_add_u32_e32 v53, 64, v53
	v_cmp_lt_i32_e32 vcc, v52, v53
	v_xor_b32_e32 v54, 32, v144
	v_mul_f32_e32 v55, v51, v51
	v_cndmask_b32_e32 v52, v144, v52, vcc
	v_cmp_lt_i32_e32 vcc, v54, v53
	v_fmac_f32_e32 v55, v50, v50
	v_lshlrev_b32_e32 v52, 2, v52
	v_cndmask_b32_e32 v53, v144, v54, vcc
	v_mul_f32_e32 v54, v49, v49
	v_fmac_f32_e32 v54, v48, v48
	v_add_f32_e32 v54, v54, v55
	ds_bpermute_b32 v55, v52, v54
	v_lshlrev_b32_e32 v53, 2, v53
	s_waitcnt lgkmcnt(0)
	v_add_f32_e32 v54, v54, v55
	ds_bpermute_b32 v55, v53, v54
	s_and_saveexec_b64 s[48:49], s[12:13]
	s_cbranch_execz .LBB0_1431
	s_waitcnt lgkmcnt(0)
	v_add_f32_e32 v54, v54, v55
	ds_write_b32 v101, v54

; template <class F>
; __device__ __forceinline__ void small_gemm_ks(LAS unsigned char* lds, const bf16_t* A, int lda, const bf16_t* Bt, int ldb, int K, int N, int a_grp_cols, int bx, int G, int tid, const F& f) {
;     ...
;     for (int t = bx; t < ntiles; t += G) {
;         const int row0 = MP + (t / ntn) * 32 + wm * 16, n0 = (t % ntn) * 64 + wn * 32;
;         const bf16_t* ap = A + (size_t)(row0 + c) * lda + (n0 >> 8) * a_grp_cols + kh * KH + 8 * g;
;         const bf16_t* bp = Bt + (size_t)(n0 + c) * ldb + kh * KH + 8 * g;
;         f32x4 acc[2] = {(f32x4){0.f, 0.f, 0.f, 0.f}, (f32x4){0.f, 0.f, 0.f, 0.f}};
; #pragma unroll 8
;         for (int k0 = 0; k0 < KH; k0 += 32) { const bf16x8 av = *(const bf16x8*)(ap + k0);
; #pragma unroll
;             for (int nt = 0; nt < 2; ++nt) { const bf16x8 bv = *(const bf16x8*)(bp + (size_t)nt * 16 * ldb + k0); acc[nt] = __builtin_amdgcn_mfma_f32_16x16x32_bf16(av, bv, acc[nt], 0, 0, 0); } }
.Lsg_hout_tile:
	s_lshr_b32 s82, s81, 4
	s_and_b32 s83, s81, 15
	s_lshl_b32 s82, s82, 5
	s_add_i32 s82, s82, 0x4000
	s_lshl_b32 s83, s83, 6
	s_lshl_b32 s59, s80, 3
	s_add_i32 s59, s59, s82
	s_mul_i32 s60, s59, 2048
	s_mul_hi_u32 s61, s59, 2048
	s_mul_i32 s62, s70, 1024
	s_add_u32 s60, s60, s62
	s_addc_u32 s61, s61, 0
	s_add_u32 s60, s60, s54
	s_addc_u32 s61, s61, s55
	s_add_u32 s60, s60, 0x3600000
	s_addc_u32 s61, s61, 0
	v_lshl_add_u64 v[110:111], s[60:61], 0, v[90:91]
	s_lshl_b32 s59, s80, 4
	s_add_i32 s59, s59, s83
	s_mul_i32 s60, s59, 2048
	s_mul_i32 s62, s70, 1024
	s_add_u32 s60, s60, s62
	s_add_u32 s60, s60, s54
	s_addc_u32 s61, s55, 0
	s_add_u32 s60, s60, 0x2a80000
	s_addc_u32 s61, s61, 0
	v_lshl_add_u64 v[112:113], s[60:61], 0, v[92:93]
	s_add_u32 s60, s60, 16384
	s_addc_u32 s61, s61, 0
	v_lshl_add_u64 v[114:115], s[60:61], 0, v[92:93]
	v_mov_b32_e32 v120, 0
	v_mov_b32_e32 v121, 0
	v_mov_b32_e32 v122, 0
	v_mov_b32_e32 v123, 0
	v_mov_b32_e32 v124, 0
	v_mov_b32_e32 v125, 0
	v_mov_b32_e32 v126, 0
	v_mov_b32_e32 v127, 0
	s_add_i32 m0, s76, 0
	s_nop 0
	global_load_lds_dwordx4 v[110:111], off
	v_lshl_add_u64 v[110:111], v[110:111], 0, s[78:79]
	s_add_i32 m0, s77, 0
	s_nop 0
	global_load_lds_dwordx4 v[112:113], off
	v_lshl_add_u64 v[112:113], v[112:113], 0, s[78:79]
	s_add_i32 m0, s77, 1024
	s_nop 0
	global_load_lds_dwordx4 v[114:115], off
	v_lshl_add_u64 v[114:115], v[114:115], 0, s[78:79]
	s_add_i32 m0, s76, 24576
	s_nop 0
	global_load_lds_dwordx4 v[110:111], off
	v_lshl_add_u64 v[110:111], v[110:111], 0, s[78:79]
	s_add_i32 m0, s77, 24576
	s_nop 0
	global_load_lds_dwordx4 v[112:113], off
	v_lshl_add_u64 v[112:113], v[112:113], 0, s[78:79]
	s_add_i32 m0, s77, 25600
	s_nop 0
	global_load_lds_dwordx4 v[114:115], off
	v_lshl_add_u64 v[114:115], v[114:115], 0, s[78:79]
	s_add_i32 m0, s76, 49152
	s_nop 0
	global_load_lds_dwordx4 v[110:111], off
	v_lshl_add_u64 v[110:111], v[110:111], 0, s[78:79]
	s_add_i32 m0, s77, 49152
	s_nop 0
	global_load_lds_dwordx4 v[112:113], off
	v_lshl_add_u64 v[112:113], v[112:113], 0, s[78:79]
	s_add_i32 m0, s77, 50176
	s_nop 0
	global_load_lds_dwordx4 v[114:115], off
	v_lshl_add_u64 v[114:115], v[114:115], 0, s[78:79]
	s_add_i32 m0, s76, 73728
	s_nop 0
	global_load_lds_dwordx4 v[110:111], off
	v_lshl_add_u64 v[110:111], v[110:111], 0, s[78:79]
	s_add_i32 m0, s77, 73728
	s_nop 0
	global_load_lds_dwordx4 v[112:113], off
	v_lshl_add_u64 v[112:113], v[112:113], 0, s[78:79]
	s_add_i32 m0, s77, 74752
	s_nop 0
	global_load_lds_dwordx4 v[114:115], off
	v_lshl_add_u64 v[114:115], v[114:115], 0, s[78:79]
	s_waitcnt vmcnt(9)
	s_barrier
	ds_read_b128 v[128:131], v96
	ds_read_b128 v[136:139], v101 offset:0
	ds_read_b128 v[144:147], v101 offset:2048
	ds_read_b128 v[132:135], v188
	ds_read_b128 v[140:143], v193 offset:0
	ds_read_b128 v[148:151], v193 offset:2048
	s_add_i32 m0, s76, 98304
	s_nop 0
	global_load_lds_dwordx4 v[110:111], off
	v_lshl_add_u64 v[110:111], v[110:111], 0, s[78:79]
	s_add_i32 m0, s77, 98304
	s_nop 0
	global_load_lds_dwordx4 v[112:113], off
	v_lshl_add_u64 v[112:113], v[112:113], 0, s[78:79]
	s_add_i32 m0, s77, 99328
	s_nop 0
	global_load_lds_dwordx4 v[114:115], off
	v_lshl_add_u64 v[114:115], v[114:115], 0, s[78:79]
	s_waitcnt lgkmcnt(3)
	v_mfma_f32_16x16x32_bf16 v[120:123], v[128:131], v[136:139], v[120:123]
	v_mfma_f32_16x16x32_bf16 v[124:127], v[128:131], v[144:147], v[124:127]
	s_waitcnt lgkmcnt(0)
	v_mfma_f32_16x16x32_bf16 v[120:123], v[132:135], v[140:143], v[120:123]
	v_mfma_f32_16x16x32_bf16 v[124:127], v[132:135], v[148:151], v[124:127]
	s_waitcnt vmcnt(9)
	s_barrier
	ds_read_b128 v[152:155], v97
	ds_read_b128 v[160:163], v102 offset:0
	ds_read_b128 v[168:171], v102 offset:2048
	ds_read_b128 v[156:159], v189
	ds_read_b128 v[164:167], v194 offset:0
	ds_read_b128 v[172:175], v194 offset:2048
	s_add_i32 m0, s76, 0
	s_nop 0
	global_load_lds_dwordx4 v[110:111], off
	v_lshl_add_u64 v[110:111], v[110:111], 0, s[78:79]
	s_add_i32 m0, s77, 0
	s_nop 0
	global_load_lds_dwordx4 v[112:113], off
	v_lshl_add_u64 v[112:113], v[112:113], 0, s[78:79]
	s_add_i32 m0, s77, 1024
	s_nop 0
	global_load_lds_dwordx4 v[114:115], off
	v_lshl_add_u64 v[114:115], v[114:115], 0, s[78:79]
	s_waitcnt lgkmcnt(3)
	v_mfma_f32_16x16x32_bf16 v[120:123], v[152:155], v[160:163], v[120:123]
	v_mfma_f32_16x16x32_bf16 v[124:127], v[152:155], v[168:171], v[124:127]
	s_waitcnt lgkmcnt(0)
	v_mfma_f32_16x16x32_bf16 v[120:123], v[156:159], v[164:167], v[120:123]
	v_mfma_f32_16x16x32_bf16 v[124:127], v[156:159], v[172:175], v[124:127]
	s_waitcnt vmcnt(9)
	s_barrier
; #define LAS __attribute__((address_space(3)))
; #define LDS_SYNC() do { asm volatile("s_waitcnt lgkmcnt(0)" ::: "memory"); __builtin_amdgcn_s_barrier(); asm volatile("" ::: "memory"); } while (0)
; template <class F>
; __device__ __forceinline__ void small_gemm_ks(LAS unsigned char* lds, const bf16_t* A, int lda, const bf16_t* Bt, int ldb, int K, int N, int a_grp_cols, int bx, int G, int tid, const F& f) {
;     ...
;         for (int k0 = 0; k0 < KH; k0 += 32) { const bf16x8 av = *(const bf16x8*)(ap + k0);
; #pragma unroll
;             for (int nt = 0; nt < 2; ++nt) { const bf16x8 bv = *(const bf16x8*)(bp + (size_t)nt * 16 * ldb + k0); acc[nt] = __builtin_amdgcn_mfma_f32_16x16x32_bf16(av, bv, acc[nt], 0, 0, 0); } }
;         if (kh == 1) { *(LAS f32x4*)(lds + ((wq * 2 + 0) * 64 + lane) * 16) = acc[0]; *(LAS f32x4*)(lds + ((wq * 2 + 1) * 64 + lane) * 16) = acc[1]; }
;         LDS_SYNC();
;         if (kh == 0) {
; #pragma unroll
;             for (int nt = 0; nt < 2; ++nt) { const f32x4 o = acc[nt] + *(const LAS f32x4*)(lds + ((wq * 2 + nt) * 64 + lane) * 16);
; #pragma unroll
;                 for (int j = 0; j < 4; ++j) f(row0 + 4 * g + j, n0 + 16 * nt + c, o[j]); }
;         }
;         LDS_SYNC();
	ds_read_b128 v[128:131], v98
	ds_read_b128 v[136:139], v103 offset:0
	ds_read_b128 v[144:147], v103 offset:2048
	ds_read_b128 v[132:135], v190
	ds_read_b128 v[140:143], v195 offset:0
	ds_read_b128 v[148:151], v195 offset:2048
	s_add_i32 m0, s76, 24576
	s_nop 0
	global_load_lds_dwordx4 v[110:111], off
	v_lshl_add_u64 v[110:111], v[110:111], 0, s[78:79]
	s_add_i32 m0, s77, 24576
	s_nop 0
	global_load_lds_dwordx4 v[112:113], off
	v_lshl_add_u64 v[112:113], v[112:113], 0, s[78:79]
	s_add_i32 m0, s77, 25600
	s_nop 0
	global_load_lds_dwordx4 v[114:115], off
	v_lshl_add_u64 v[114:115], v[114:115], 0, s[78:79]
	s_waitcnt lgkmcnt(3)
	v_mfma_f32_16x16x32_bf16 v[120:123], v[128:131], v[136:139], v[120:123]
	v_mfma_f32_16x16x32_bf16 v[124:127], v[128:131], v[144:147], v[124:127]
	s_waitcnt lgkmcnt(0)
	v_mfma_f32_16x16x32_bf16 v[120:123], v[132:135], v[140:143], v[120:123]
	v_mfma_f32_16x16x32_bf16 v[124:127], v[132:135], v[148:151], v[124:127]
	s_waitcnt vmcnt(9)
	s_barrier
	ds_read_b128 v[152:155], v99
	ds_read_b128 v[160:163], v104 offset:0
	ds_read_b128 v[168:171], v104 offset:2048
	ds_read_b128 v[156:159], v191
	ds_read_b128 v[164:167], v196 offset:0
	ds_read_b128 v[172:175], v196 offset:2048
	s_add_i32 m0, s76, 49152
	s_nop 0
	global_load_lds_dwordx4 v[110:111], off
	v_lshl_add_u64 v[110:111], v[110:111], 0, s[78:79]
	s_add_i32 m0, s77, 49152
	s_nop 0
	global_load_lds_dwordx4 v[112:113], off
	v_lshl_add_u64 v[112:113], v[112:113], 0, s[78:79]
	s_add_i32 m0, s77, 50176
	s_nop 0
	global_load_lds_dwordx4 v[114:115], off
	v_lshl_add_u64 v[114:115], v[114:115], 0, s[78:79]
	s_waitcnt lgkmcnt(3)
	v_mfma_f32_16x16x32_bf16 v[120:123], v[152:155], v[160:163], v[120:123]
	v_mfma_f32_16x16x32_bf16 v[124:127], v[152:155], v[168:171], v[124:127]
	s_waitcnt lgkmcnt(0)
	v_mfma_f32_16x16x32_bf16 v[120:123], v[156:159], v[164:167], v[120:123]
	v_mfma_f32_16x16x32_bf16 v[124:127], v[156:159], v[172:175], v[124:127]
	s_waitcnt vmcnt(9)
	s_barrier
	ds_read_b128 v[128:131], v100
	ds_read_b128 v[136:139], v105 offset:0
	ds_read_b128 v[144:147], v105 offset:2048
	ds_read_b128 v[132:135], v192
	ds_read_b128 v[140:143], v197 offset:0
	ds_read_b128 v[148:151], v197 offset:2048
	s_waitcnt lgkmcnt(3)
	v_mfma_f32_16x16x32_bf16 v[120:123], v[128:131], v[136:139], v[120:123]
	v_mfma_f32_16x16x32_bf16 v[124:127], v[128:131], v[144:147], v[124:127]
	s_waitcnt lgkmcnt(0)
	v_mfma_f32_16x16x32_bf16 v[120:123], v[132:135], v[140:143], v[120:123]
	v_mfma_f32_16x16x32_bf16 v[124:127], v[132:135], v[148:151], v[124:127]
	s_waitcnt vmcnt(6)
	s_barrier
	ds_read_b128 v[152:155], v96
	ds_read_b128 v[160:163], v101 offset:0
	ds_read_b128 v[168:171], v101 offset:2048
	ds_read_b128 v[156:159], v188
	ds_read_b128 v[164:167], v193 offset:0
	ds_read_b128 v[172:175], v193 offset:2048
	s_waitcnt lgkmcnt(3)
	v_mfma_f32_16x16x32_bf16 v[120:123], v[152:155], v[160:163], v[120:123]
	v_mfma_f32_16x16x32_bf16 v[124:127], v[152:155], v[168:171], v[124:127]
	s_waitcnt lgkmcnt(0)
	v_mfma_f32_16x16x32_bf16 v[120:123], v[156:159], v[164:167], v[120:123]
	v_mfma_f32_16x16x32_bf16 v[124:127], v[156:159], v[172:175], v[124:127]
	s_waitcnt vmcnt(3)
	s_barrier
	ds_read_b128 v[128:131], v97
	ds_read_b128 v[136:139], v102 offset:0
	ds_read_b128 v[144:147], v102 offset:2048
	ds_read_b128 v[132:135], v189
	ds_read_b128 v[140:143], v194 offset:0
	ds_read_b128 v[148:151], v194 offset:2048
	s_waitcnt lgkmcnt(3)
	v_mfma_f32_16x16x32_bf16 v[120:123], v[128:131], v[136:139], v[120:123]
	v_mfma_f32_16x16x32_bf16 v[124:127], v[128:131], v[144:147], v[124:127]
	s_waitcnt lgkmcnt(0)
	v_mfma_f32_16x16x32_bf16 v[120:123], v[132:135], v[140:143], v[120:123]
	v_mfma_f32_16x16x32_bf16 v[124:127], v[132:135], v[148:151], v[124:127]
	s_waitcnt vmcnt(0)
	s_barrier
	ds_read_b128 v[152:155], v98
	ds_read_b128 v[160:163], v103 offset:0
	ds_read_b128 v[168:171], v103 offset:2048
	ds_read_b128 v[156:159], v190
	ds_read_b128 v[164:167], v195 offset:0
	ds_read_b128 v[172:175], v195 offset:2048
	s_waitcnt lgkmcnt(3)
	v_mfma_f32_16x16x32_bf16 v[120:123], v[152:155], v[160:163], v[120:123]
	v_mfma_f32_16x16x32_bf16 v[124:127], v[152:155], v[168:171], v[124:127]
	s_waitcnt lgkmcnt(0)
	v_mfma_f32_16x16x32_bf16 v[120:123], v[156:159], v[164:167], v[120:123]
	v_mfma_f32_16x16x32_bf16 v[124:127], v[156:159], v[172:175], v[124:127]
	s_barrier
	s_lshl_b32 s59, s82, 11
	s_lshl_b32 s62, s83, 1
	s_add_i32 s59, s59, s62
	s_add_u32 s60, s54, s59
	s_addc_u32 s61, s55, 0
	s_add_u32 s60, s60, 0x5700000
	s_addc_u32 s61, s61, 0
	v_lshl_add_u64 v[176:177], s[60:61], 0, v[106:107]
	s_mov_b32 s62, 0x1000
	s_mov_b32 s63, 0
	v_lshl_add_u64 v[178:179], v[176:177], 0, s[62:63]
	s_cmp_eq_u32 s70, 0
	s_cbranch_scc1 .Lsg_hout_lo
	s_nop 4
	ds_write_b128 v109, v[120:123]
	ds_write_b128 v109, v[124:127] offset:1024
	s_waitcnt lgkmcnt(0)
	s_barrier
	s_branch .Lsg_hout_done

; template <class F>
; __device__ __forceinline__ void small_gemm_ks(LAS unsigned char* lds, const bf16_t* A, int lda, const bf16_t* Bt, int ldb, int K, int N, int a_grp_cols, int bx, int G, int tid, const F& f) {
;     ...
;     for (int t = bx; t < ntiles; t += G) {
;         const int row0 = MP + (t / ntn) * 32 + wm * 16, n0 = (t % ntn) * 64 + wn * 32;
;         const bf16_t* ap = A + (size_t)(row0 + c) * lda + (n0 >> 8) * a_grp_cols + kh * KH + 8 * g;
;         const bf16_t* bp = Bt + (size_t)(n0 + c) * ldb + kh * KH + 8 * g;
;         f32x4 acc[2] = {(f32x4){0.f, 0.f, 0.f, 0.f}, (f32x4){0.f, 0.f, 0.f, 0.f}};
; #pragma unroll 8
;         for (int k0 = 0; k0 < KH; k0 += 32) { const bf16x8 av = *(const bf16x8*)(ap + k0);
; #pragma unroll
;             for (int nt = 0; nt < 2; ++nt) { const bf16x8 bv = *(const bf16x8*)(bp + (size_t)nt * 16 * ldb + k0); acc[nt] = __builtin_amdgcn_mfma_f32_16x16x32_bf16(av, bv, acc[nt], 0, 0, 0); } }
.Lsg_dn1_tile:
	s_lshr_b32 s82, s81, 4
	s_and_b32 s83, s81, 15
	s_lshl_b32 s82, s82, 5
	s_add_i32 s82, s82, 0x4000
	s_lshl_b32 s83, s83, 6
	s_lshl_b32 s59, s80, 3
	s_add_i32 s59, s59, s82
	s_mul_i32 s60, s59, 5632
	s_mul_hi_u32 s61, s59, 5632
	s_mul_i32 s62, s70, 2816
	s_add_u32 s60, s60, s62
	s_addc_u32 s61, s61, 0
	s_add_u32 s60, s60, s54
	s_addc_u32 s61, s61, s55
	s_add_u32 s60, s60, 0x9900000
	s_addc_u32 s61, s61, 0
	v_lshl_add_u64 v[110:111], s[60:61], 0, v[90:91]
	s_lshl_b32 s59, s80, 4
	s_add_i32 s59, s59, s83
	s_mul_i32 s60, s59, 5632
	s_mul_i32 s62, s70, 2816
	s_add_u32 s60, s60, s62
	s_add_u32 s60, s60, s54
	s_addc_u32 s61, s55, 0
	s_add_u32 s60, s60, 0x1d00000
	s_addc_u32 s61, s61, 0
	v_lshl_add_u64 v[112:113], s[60:61], 0, v[92:93]
	s_add_u32 s60, s60, 45056
	s_addc_u32 s61, s61, 0
	v_lshl_add_u64 v[114:115], s[60:61], 0, v[92:93]
	v_mov_b32_e32 v120, 0
	v_mov_b32_e32 v121, 0
	v_mov_b32_e32 v122, 0
	v_mov_b32_e32 v123, 0
	v_mov_b32_e32 v124, 0
	v_mov_b32_e32 v125, 0
	v_mov_b32_e32 v126, 0
	v_mov_b32_e32 v127, 0
	s_add_i32 m0, s76, 0
	s_nop 0
	global_load_lds_dwordx4 v[110:111], off
	v_lshl_add_u64 v[110:111], v[110:111], 0, s[78:79]
	s_add_i32 m0, s77, 0
	s_nop 0
	global_load_lds_dwordx4 v[112:113], off
	v_lshl_add_u64 v[112:113], v[112:113], 0, s[78:79]
	s_add_i32 m0, s77, 1024
	s_nop 0
	global_load_lds_dwordx4 v[114:115], off
	v_lshl_add_u64 v[114:115], v[114:115], 0, s[78:79]
	s_add_i32 m0, s76, 24576
	s_nop 0
	global_load_lds_dwordx4 v[110:111], off
	v_lshl_add_u64 v[110:111], v[110:111], 0, s[78:79]
	s_add_i32 m0, s77, 24576
	s_nop 0
	global_load_lds_dwordx4 v[112:113], off
	v_lshl_add_u64 v[112:113], v[112:113], 0, s[78:79]
	s_add_i32 m0, s77, 25600
	s_nop 0
	global_load_lds_dwordx4 v[114:115], off
	v_lshl_add_u64 v[114:115], v[114:115], 0, s[78:79]
	s_add_i32 m0, s76, 49152
	s_nop 0
	global_load_lds_dwordx4 v[110:111], off
	v_lshl_add_u64 v[110:111], v[110:111], 0, s[78:79]
	s_add_i32 m0, s77, 49152
	s_nop 0
	global_load_lds_dwordx4 v[112:113], off
	v_lshl_add_u64 v[112:113], v[112:113], 0, s[78:79]
	s_add_i32 m0, s77, 50176
	s_nop 0
	global_load_lds_dwordx4 v[114:115], off
	v_lshl_add_u64 v[114:115], v[114:115], 0, s[78:79]
	s_add_i32 m0, s76, 73728
	s_nop 0
	global_load_lds_dwordx4 v[110:111], off
	v_lshl_add_u64 v[110:111], v[110:111], 0, s[78:79]
	s_add_i32 m0, s77, 73728
	s_nop 0
	global_load_lds_dwordx4 v[112:113], off
	v_lshl_add_u64 v[112:113], v[112:113], 0, s[78:79]
	s_add_i32 m0, s77, 74752
	s_nop 0
	global_load_lds_dwordx4 v[114:115], off
	v_lshl_add_u64 v[114:115], v[114:115], 0, s[78:79]
	s_waitcnt vmcnt(9)
	s_barrier
	ds_read_b128 v[128:131], v96
	ds_read_b128 v[136:139], v101 offset:0
	ds_read_b128 v[144:147], v101 offset:2048
	ds_read_b128 v[132:135], v188
	ds_read_b128 v[140:143], v193 offset:0
	ds_read_b128 v[148:151], v193 offset:2048
	s_add_i32 m0, s76, 98304
	s_nop 0
	global_load_lds_dwordx4 v[110:111], off
	v_lshl_add_u64 v[110:111], v[110:111], 0, s[78:79]
	s_add_i32 m0, s77, 98304
	s_nop 0
	global_load_lds_dwordx4 v[112:113], off
	v_lshl_add_u64 v[112:113], v[112:113], 0, s[78:79]
	s_add_i32 m0, s77, 99328
	s_nop 0
	global_load_lds_dwordx4 v[114:115], off
	v_lshl_add_u64 v[114:115], v[114:115], 0, s[78:79]
	s_waitcnt lgkmcnt(3)
	v_mfma_f32_16x16x32_bf16 v[120:123], v[128:131], v[136:139], v[120:123]
	v_mfma_f32_16x16x32_bf16 v[124:127], v[128:131], v[144:147], v[124:127]
	s_waitcnt lgkmcnt(0)
	v_mfma_f32_16x16x32_bf16 v[120:123], v[132:135], v[140:143], v[120:123]
	v_mfma_f32_16x16x32_bf16 v[124:127], v[132:135], v[148:151], v[124:127]
	s_waitcnt vmcnt(9)
	s_barrier
	ds_read_b128 v[152:155], v97
	ds_read_b128 v[160:163], v102 offset:0
	ds_read_b128 v[168:171], v102 offset:2048
	ds_read_b128 v[156:159], v189
	ds_read_b128 v[164:167], v194 offset:0
	ds_read_b128 v[172:175], v194 offset:2048
	s_add_i32 m0, s76, 0
	s_nop 0
	global_load_lds_dwordx4 v[110:111], off
	v_lshl_add_u64 v[110:111], v[110:111], 0, s[78:79]
	s_add_i32 m0, s77, 0
	s_nop 0
	global_load_lds_dwordx4 v[112:113], off
	v_lshl_add_u64 v[112:113], v[112:113], 0, s[78:79]
	s_add_i32 m0, s77, 1024
	s_nop 0
	global_load_lds_dwordx4 v[114:115], off
	v_lshl_add_u64 v[114:115], v[114:115], 0, s[78:79]
	s_waitcnt lgkmcnt(3)
	v_mfma_f32_16x16x32_bf16 v[120:123], v[152:155], v[160:163], v[120:123]
	v_mfma_f32_16x16x32_bf16 v[124:127], v[152:155], v[168:171], v[124:127]
	s_waitcnt lgkmcnt(0)
	v_mfma_f32_16x16x32_bf16 v[120:123], v[156:159], v[164:167], v[120:123]
	v_mfma_f32_16x16x32_bf16 v[124:127], v[156:159], v[172:175], v[124:127]
	s_waitcnt vmcnt(9)
	s_barrier
	ds_read_b128 v[128:131], v98
	ds_read_b128 v[136:139], v103 offset:0
	ds_read_b128 v[144:147], v103 offset:2048
	ds_read_b128 v[132:135], v190
	ds_read_b128 v[140:143], v195 offset:0
	ds_read_b128 v[148:151], v195 offset:2048
	s_add_i32 m0, s76, 24576
	s_nop 0
	global_load_lds_dwordx4 v[110:111], off
	v_lshl_add_u64 v[110:111], v[110:111], 0, s[78:79]
	s_add_i32 m0, s77, 24576
	s_nop 0
	global_load_lds_dwordx4 v[112:113], off
	v_lshl_add_u64 v[112:113], v[112:113], 0, s[78:79]
	s_add_i32 m0, s77, 25600
	s_nop 0
	global_load_lds_dwordx4 v[114:115], off
	v_lshl_add_u64 v[114:115], v[114:115], 0, s[78:79]
	s_waitcnt lgkmcnt(3)
	v_mfma_f32_16x16x32_bf16 v[120:123], v[128:131], v[136:139], v[120:123]
	v_mfma_f32_16x16x32_bf16 v[124:127], v[128:131], v[144:147], v[124:127]
	s_waitcnt lgkmcnt(0)
	v_mfma_f32_16x16x32_bf16 v[120:123], v[132:135], v[140:143], v[120:123]
	v_mfma_f32_16x16x32_bf16 v[124:127], v[132:135], v[148:151], v[124:127]
	s_waitcnt vmcnt(9)
	s_barrier
; template <class F>
; __device__ __forceinline__ void small_gemm_ks(LAS unsigned char* lds, const bf16_t* A, int lda, const bf16_t* Bt, int ldb, int K, int N, int a_grp_cols, int bx, int G, int tid, const F& f) {
;     ...
;         for (int k0 = 0; k0 < KH; k0 += 32) { const bf16x8 av = *(const bf16x8*)(ap + k0);
; #pragma unroll
;             for (int nt = 0; nt < 2; ++nt) { const bf16x8 bv = *(const bf16x8*)(bp + (size_t)nt * 16 * ldb + k0); acc[nt] = __builtin_amdgcn_mfma_f32_16x16x32_bf16(av, bv, acc[nt], 0, 0, 0); } }
	ds_read_b128 v[152:155], v99
	ds_read_b128 v[160:163], v104 offset:0
	ds_read_b128 v[168:171], v104 offset:2048
	ds_read_b128 v[156:159], v191
	ds_read_b128 v[164:167], v196 offset:0
	ds_read_b128 v[172:175], v196 offset:2048
	s_add_i32 m0, s76, 49152
	s_nop 0
	global_load_lds_dwordx4 v[110:111], off
	v_lshl_add_u64 v[110:111], v[110:111], 0, s[78:79]
	s_add_i32 m0, s77, 49152
	s_nop 0
	global_load_lds_dwordx4 v[112:113], off
	v_lshl_add_u64 v[112:113], v[112:113], 0, s[78:79]
	s_add_i32 m0, s77, 50176
	s_nop 0
	global_load_lds_dwordx4 v[114:115], off
	v_lshl_add_u64 v[114:115], v[114:115], 0, s[78:79]
	s_waitcnt lgkmcnt(3)
	v_mfma_f32_16x16x32_bf16 v[120:123], v[152:155], v[160:163], v[120:123]
	v_mfma_f32_16x16x32_bf16 v[124:127], v[152:155], v[168:171], v[124:127]
	s_waitcnt lgkmcnt(0)
	v_mfma_f32_16x16x32_bf16 v[120:123], v[156:159], v[164:167], v[120:123]
	v_mfma_f32_16x16x32_bf16 v[124:127], v[156:159], v[172:175], v[124:127]
	s_waitcnt vmcnt(9)
	s_barrier
	ds_read_b128 v[128:131], v100
	ds_read_b128 v[136:139], v105 offset:0
	ds_read_b128 v[144:147], v105 offset:2048
	ds_read_b128 v[132:135], v192
	ds_read_b128 v[140:143], v197 offset:0
	ds_read_b128 v[148:151], v197 offset:2048
	s_add_i32 m0, s76, 73728
	s_nop 0
	global_load_lds_dwordx4 v[110:111], off
	v_lshl_add_u64 v[110:111], v[110:111], 0, s[78:79]
	s_add_i32 m0, s77, 73728
	s_nop 0
	global_load_lds_dwordx4 v[112:113], off
	v_lshl_add_u64 v[112:113], v[112:113], 0, s[78:79]
	s_add_i32 m0, s77, 74752
	s_nop 0
	global_load_lds_dwordx4 v[114:115], off
	v_lshl_add_u64 v[114:115], v[114:115], 0, s[78:79]
	s_waitcnt lgkmcnt(3)
	v_mfma_f32_16x16x32_bf16 v[120:123], v[128:131], v[136:139], v[120:123]
	v_mfma_f32_16x16x32_bf16 v[124:127], v[128:131], v[144:147], v[124:127]
	s_waitcnt lgkmcnt(0)
	v_mfma_f32_16x16x32_bf16 v[120:123], v[132:135], v[140:143], v[120:123]
	v_mfma_f32_16x16x32_bf16 v[124:127], v[132:135], v[148:151], v[124:127]
	s_waitcnt vmcnt(9)
	s_barrier
	ds_read_b128 v[152:155], v96
	ds_read_b128 v[160:163], v101 offset:0
	ds_read_b128 v[168:171], v101 offset:2048
	ds_read_b128 v[156:159], v188
	ds_read_b128 v[164:167], v193 offset:0
	ds_read_b128 v[172:175], v193 offset:2048
	s_add_i32 m0, s76, 98304
	s_nop 0
	global_load_lds_dwordx4 v[110:111], off
	v_lshl_add_u64 v[110:111], v[110:111], 0, s[78:79]
	s_add_i32 m0, s77, 98304
	s_nop 0
	global_load_lds_dwordx4 v[112:113], off
	v_lshl_add_u64 v[112:113], v[112:113], 0, s[78:79]
	s_add_i32 m0, s77, 99328
	s_nop 0
	global_load_lds_dwordx4 v[114:115], off
	v_lshl_add_u64 v[114:115], v[114:115], 0, s[78:79]
	s_waitcnt lgkmcnt(3)
	v_mfma_f32_16x16x32_bf16 v[120:123], v[152:155], v[160:163], v[120:123]
	v_mfma_f32_16x16x32_bf16 v[124:127], v[152:155], v[168:171], v[124:127]
	s_waitcnt lgkmcnt(0)
	v_mfma_f32_16x16x32_bf16 v[120:123], v[156:159], v[164:167], v[120:123]
	v_mfma_f32_16x16x32_bf16 v[124:127], v[156:159], v[172:175], v[124:127]
	s_waitcnt vmcnt(9)
	s_barrier
	ds_read_b128 v[128:131], v97
	ds_read_b128 v[136:139], v102 offset:0
	ds_read_b128 v[144:147], v102 offset:2048
	ds_read_b128 v[132:135], v189
	ds_read_b128 v[140:143], v194 offset:0
	ds_read_b128 v[148:151], v194 offset:2048
	s_add_i32 m0, s76, 0
	s_nop 0
	global_load_lds_dwordx4 v[110:111], off
	v_lshl_add_u64 v[110:111], v[110:111], 0, s[78:79]
	s_add_i32 m0, s77, 0
	s_nop 0
	global_load_lds_dwordx4 v[112:113], off
	v_lshl_add_u64 v[112:113], v[112:113], 0, s[78:79]
	s_add_i32 m0, s77, 1024
	s_nop 0
	global_load_lds_dwordx4 v[114:115], off
	v_lshl_add_u64 v[114:115], v[114:115], 0, s[78:79]
	s_waitcnt lgkmcnt(3)
	v_mfma_f32_16x16x32_bf16 v[120:123], v[128:131], v[136:139], v[120:123]
	v_mfma_f32_16x16x32_bf16 v[124:127], v[128:131], v[144:147], v[124:127]
	s_waitcnt lgkmcnt(0)
	v_mfma_f32_16x16x32_bf16 v[120:123], v[132:135], v[140:143], v[120:123]
	v_mfma_f32_16x16x32_bf16 v[124:127], v[132:135], v[148:151], v[124:127]
	s_waitcnt vmcnt(9)
	s_barrier
	ds_read_b128 v[152:155], v98
	ds_read_b128 v[160:163], v103 offset:0
	ds_read_b128 v[168:171], v103 offset:2048
	ds_read_b128 v[156:159], v190
	ds_read_b128 v[164:167], v195 offset:0
	ds_read_b128 v[172:175], v195 offset:2048
	s_add_i32 m0, s76, 24576
	s_nop 0
	global_load_lds_dwordx4 v[110:111], off
	v_lshl_add_u64 v[110:111], v[110:111], 0, s[78:79]
	s_add_i32 m0, s77, 24576
	s_nop 0
	global_load_lds_dwordx4 v[112:113], off
	v_lshl_add_u64 v[112:113], v[112:113], 0, s[78:79]
	s_add_i32 m0, s77, 25600
	s_nop 0
	global_load_lds_dwordx4 v[114:115], off
	v_lshl_add_u64 v[114:115], v[114:115], 0, s[78:79]
	s_waitcnt lgkmcnt(3)
	v_mfma_f32_16x16x32_bf16 v[120:123], v[152:155], v[160:163], v[120:123]
	v_mfma_f32_16x16x32_bf16 v[124:127], v[152:155], v[168:171], v[124:127]
	s_waitcnt lgkmcnt(0)
	v_mfma_f32_16x16x32_bf16 v[120:123], v[156:159], v[164:167], v[120:123]
	v_mfma_f32_16x16x32_bf16 v[124:127], v[156:159], v[172:175], v[124:127]
	s_waitcnt vmcnt(9)
	s_barrier
	ds_read_b128 v[128:131], v99
	ds_read_b128 v[136:139], v104 offset:0
	ds_read_b128 v[144:147], v104 offset:2048
	ds_read_b128 v[132:135], v191
	ds_read_b128 v[140:143], v196 offset:0
	ds_read_b128 v[148:151], v196 offset:2048
	s_add_i32 m0, s76, 49152
	s_nop 0
	global_load_lds_dwordx4 v[110:111], off
	v_lshl_add_u64 v[110:111], v[110:111], 0, s[78:79]
	s_add_i32 m0, s77, 49152
	s_nop 0
	global_load_lds_dwordx4 v[112:113], off
	v_lshl_add_u64 v[112:113], v[112:113], 0, s[78:79]
	s_add_i32 m0, s77, 50176
	s_nop 0
	global_load_lds_dwordx4 v[114:115], off
	v_lshl_add_u64 v[114:115], v[114:115], 0, s[78:79]
	s_waitcnt lgkmcnt(3)
	v_mfma_f32_16x16x32_bf16 v[120:123], v[128:131], v[136:139], v[120:123]
	v_mfma_f32_16x16x32_bf16 v[124:127], v[128:131], v[144:147], v[124:127]
	s_waitcnt lgkmcnt(0)
	v_mfma_f32_16x16x32_bf16 v[120:123], v[132:135], v[140:143], v[120:123]
	v_mfma_f32_16x16x32_bf16 v[124:127], v[132:135], v[148:151], v[124:127]
	s_waitcnt vmcnt(9)
	s_barrier
; template <class F>
; __device__ __forceinline__ void small_gemm_ks(LAS unsigned char* lds, const bf16_t* A, int lda, const bf16_t* Bt, int ldb, int K, int N, int a_grp_cols, int bx, int G, int tid, const F& f) {
;     ...
;         for (int k0 = 0; k0 < KH; k0 += 32) { const bf16x8 av = *(const bf16x8*)(ap + k0);
; #pragma unroll
;             for (int nt = 0; nt < 2; ++nt) { const bf16x8 bv = *(const bf16x8*)(bp + (size_t)nt * 16 * ldb + k0); acc[nt] = __builtin_amdgcn_mfma_f32_16x16x32_bf16(av, bv, acc[nt], 0, 0, 0); } }
	ds_read_b128 v[152:155], v100
	ds_read_b128 v[160:163], v105 offset:0
	ds_read_b128 v[168:171], v105 offset:2048
	ds_read_b128 v[156:159], v192
	ds_read_b128 v[164:167], v197 offset:0
	ds_read_b128 v[172:175], v197 offset:2048
	s_add_i32 m0, s76, 73728
	s_nop 0
	global_load_lds_dwordx4 v[110:111], off
	v_lshl_add_u64 v[110:111], v[110:111], 0, s[78:79]
	s_add_i32 m0, s77, 73728
	s_nop 0
	global_load_lds_dwordx4 v[112:113], off
	v_lshl_add_u64 v[112:113], v[112:113], 0, s[78:79]
	s_add_i32 m0, s77, 74752
	s_nop 0
	global_load_lds_dwordx4 v[114:115], off
	v_lshl_add_u64 v[114:115], v[114:115], 0, s[78:79]
	s_waitcnt lgkmcnt(3)
	v_mfma_f32_16x16x32_bf16 v[120:123], v[152:155], v[160:163], v[120:123]
	v_mfma_f32_16x16x32_bf16 v[124:127], v[152:155], v[168:171], v[124:127]
	s_waitcnt lgkmcnt(0)
	v_mfma_f32_16x16x32_bf16 v[120:123], v[156:159], v[164:167], v[120:123]
	v_mfma_f32_16x16x32_bf16 v[124:127], v[156:159], v[172:175], v[124:127]
	s_waitcnt vmcnt(9)
	s_barrier
	ds_read_b128 v[128:131], v96
	ds_read_b128 v[136:139], v101 offset:0
	ds_read_b128 v[144:147], v101 offset:2048
	ds_read_b128 v[132:135], v188
	ds_read_b128 v[140:143], v193 offset:0
	ds_read_b128 v[148:151], v193 offset:2048
	s_add_i32 m0, s76, 98304
	s_nop 0
	global_load_lds_dwordx4 v[110:111], off
	v_lshl_add_u64 v[110:111], v[110:111], 0, s[78:79]
	s_add_i32 m0, s77, 98304
	s_nop 0
	global_load_lds_dwordx4 v[112:113], off
	v_lshl_add_u64 v[112:113], v[112:113], 0, s[78:79]
	s_add_i32 m0, s77, 99328
	s_nop 0
	global_load_lds_dwordx4 v[114:115], off
	v_lshl_add_u64 v[114:115], v[114:115], 0, s[78:79]
	s_waitcnt lgkmcnt(3)
	v_mfma_f32_16x16x32_bf16 v[120:123], v[128:131], v[136:139], v[120:123]
	v_mfma_f32_16x16x32_bf16 v[124:127], v[128:131], v[144:147], v[124:127]
	s_waitcnt lgkmcnt(0)
	v_mfma_f32_16x16x32_bf16 v[120:123], v[132:135], v[140:143], v[120:123]
	v_mfma_f32_16x16x32_bf16 v[124:127], v[132:135], v[148:151], v[124:127]
	s_waitcnt vmcnt(9)
	s_barrier
	ds_read_b128 v[152:155], v97
	ds_read_b128 v[160:163], v102 offset:0
	ds_read_b128 v[168:171], v102 offset:2048
	ds_read_b128 v[156:159], v189
	ds_read_b128 v[164:167], v194 offset:0
	ds_read_b128 v[172:175], v194 offset:2048
	s_add_i32 m0, s76, 0
	s_nop 0
	global_load_lds_dwordx4 v[110:111], off
	v_lshl_add_u64 v[110:111], v[110:111], 0, s[78:79]
	s_add_i32 m0, s77, 0
	s_nop 0
	global_load_lds_dwordx4 v[112:113], off
	v_lshl_add_u64 v[112:113], v[112:113], 0, s[78:79]
	s_add_i32 m0, s77, 1024
	s_nop 0
	global_load_lds_dwordx4 v[114:115], off
	v_lshl_add_u64 v[114:115], v[114:115], 0, s[78:79]
	s_waitcnt lgkmcnt(3)
	v_mfma_f32_16x16x32_bf16 v[120:123], v[152:155], v[160:163], v[120:123]
	v_mfma_f32_16x16x32_bf16 v[124:127], v[152:155], v[168:171], v[124:127]
	s_waitcnt lgkmcnt(0)
	v_mfma_f32_16x16x32_bf16 v[120:123], v[156:159], v[164:167], v[120:123]
	v_mfma_f32_16x16x32_bf16 v[124:127], v[156:159], v[172:175], v[124:127]
	s_waitcnt vmcnt(9)
	s_barrier
	ds_read_b128 v[128:131], v98
	ds_read_b128 v[136:139], v103 offset:0
	ds_read_b128 v[144:147], v103 offset:2048
	ds_read_b128 v[132:135], v190
	ds_read_b128 v[140:143], v195 offset:0
	ds_read_b128 v[148:151], v195 offset:2048
	s_add_i32 m0, s76, 24576
	s_nop 0
	global_load_lds_dwordx4 v[110:111], off
	v_lshl_add_u64 v[110:111], v[110:111], 0, s[78:79]
	s_add_i32 m0, s77, 24576
	s_nop 0
	global_load_lds_dwordx4 v[112:113], off
	v_lshl_add_u64 v[112:113], v[112:113], 0, s[78:79]
	s_add_i32 m0, s77, 25600
	s_nop 0
	global_load_lds_dwordx4 v[114:115], off
	v_lshl_add_u64 v[114:115], v[114:115], 0, s[78:79]
	s_waitcnt lgkmcnt(3)
	v_mfma_f32_16x16x32_bf16 v[120:123], v[128:131], v[136:139], v[120:123]
	v_mfma_f32_16x16x32_bf16 v[124:127], v[128:131], v[144:147], v[124:127]
	s_waitcnt lgkmcnt(0)
	v_mfma_f32_16x16x32_bf16 v[120:123], v[132:135], v[140:143], v[120:123]
	v_mfma_f32_16x16x32_bf16 v[124:127], v[132:135], v[148:151], v[124:127]
	s_waitcnt vmcnt(9)
	s_barrier
	ds_read_b128 v[152:155], v99
	ds_read_b128 v[160:163], v104 offset:0
	ds_read_b128 v[168:171], v104 offset:2048
	ds_read_b128 v[156:159], v191
	ds_read_b128 v[164:167], v196 offset:0
	ds_read_b128 v[172:175], v196 offset:2048
	s_add_i32 m0, s76, 49152
	s_nop 0
	global_load_lds_dwordx4 v[110:111], off
	v_lshl_add_u64 v[110:111], v[110:111], 0, s[78:79]
	s_add_i32 m0, s77, 49152
	s_nop 0
	global_load_lds_dwordx4 v[112:113], off
	v_lshl_add_u64 v[112:113], v[112:113], 0, s[78:79]
	s_add_i32 m0, s77, 50176
	s_nop 0
	global_load_lds_dwordx4 v[114:115], off
	v_lshl_add_u64 v[114:115], v[114:115], 0, s[78:79]
	s_waitcnt lgkmcnt(3)
	v_mfma_f32_16x16x32_bf16 v[120:123], v[152:155], v[160:163], v[120:123]
	v_mfma_f32_16x16x32_bf16 v[124:127], v[152:155], v[168:171], v[124:127]
	s_waitcnt lgkmcnt(0)
	v_mfma_f32_16x16x32_bf16 v[120:123], v[156:159], v[164:167], v[120:123]
	v_mfma_f32_16x16x32_bf16 v[124:127], v[156:159], v[172:175], v[124:127]
	s_waitcnt vmcnt(9)
	s_barrier
	ds_read_b128 v[128:131], v100
	ds_read_b128 v[136:139], v105 offset:0
	ds_read_b128 v[144:147], v105 offset:2048
	ds_read_b128 v[132:135], v192
	ds_read_b128 v[140:143], v197 offset:0
	ds_read_b128 v[148:151], v197 offset:2048
	s_add_i32 m0, s76, 73728
	s_nop 0
	global_load_lds_dwordx4 v[110:111], off
	v_lshl_add_u64 v[110:111], v[110:111], 0, s[78:79]
	s_add_i32 m0, s77, 73728
	s_nop 0
	global_load_lds_dwordx4 v[112:113], off
	v_lshl_add_u64 v[112:113], v[112:113], 0, s[78:79]
	s_add_i32 m0, s77, 74752
	s_nop 0
	global_load_lds_dwordx4 v[114:115], off
	v_lshl_add_u64 v[114:115], v[114:115], 0, s[78:79]
	s_waitcnt lgkmcnt(3)
	v_mfma_f32_16x16x32_bf16 v[120:123], v[128:131], v[136:139], v[120:123]
	v_mfma_f32_16x16x32_bf16 v[124:127], v[128:131], v[144:147], v[124:127]
	s_waitcnt lgkmcnt(0)
	v_mfma_f32_16x16x32_bf16 v[120:123], v[132:135], v[140:143], v[120:123]
	v_mfma_f32_16x16x32_bf16 v[124:127], v[132:135], v[148:151], v[124:127]
	s_waitcnt vmcnt(9)
	s_barrier
; #define LAS __attribute__((address_space(3)))
; #define LDS_SYNC() do { asm volatile("s_waitcnt lgkmcnt(0)" ::: "memory"); __builtin_amdgcn_s_barrier(); asm volatile("" ::: "memory"); } while (0)
; template <class F>
; __device__ __forceinline__ void small_gemm_ks(LAS unsigned char* lds, const bf16_t* A, int lda, const bf16_t* Bt, int ldb, int K, int N, int a_grp_cols, int bx, int G, int tid, const F& f) {
;     ...
;         for (int k0 = 0; k0 < KH; k0 += 32) { const bf16x8 av = *(const bf16x8*)(ap + k0);
; #pragma unroll
;             for (int nt = 0; nt < 2; ++nt) { const bf16x8 bv = *(const bf16x8*)(bp + (size_t)nt * 16 * ldb + k0); acc[nt] = __builtin_amdgcn_mfma_f32_16x16x32_bf16(av, bv, acc[nt], 0, 0, 0); } }
;         if (kh == 1) { *(LAS f32x4*)(lds + ((wq * 2 + 0) * 64 + lane) * 16) = acc[0]; *(LAS f32x4*)(lds + ((wq * 2 + 1) * 64 + lane) * 16) = acc[1]; }
;         LDS_SYNC();
;         if (kh == 0) {
; #pragma unroll
;             for (int nt = 0; nt < 2; ++nt) { const f32x4 o = acc[nt] + *(const LAS f32x4*)(lds + ((wq * 2 + nt) * 64 + lane) * 16);
; #pragma unroll
;                 for (int j = 0; j < 4; ++j) f(row0 + 4 * g + j, n0 + 16 * nt + c, o[j]); }
;         }
;         LDS_SYNC();
	ds_read_b128 v[152:155], v96
	ds_read_b128 v[160:163], v101 offset:0
	ds_read_b128 v[168:171], v101 offset:2048
	ds_read_b128 v[156:159], v188
	ds_read_b128 v[164:167], v193 offset:0
	ds_read_b128 v[172:175], v193 offset:2048
	s_add_i32 m0, s76, 98304
	s_nop 0
	global_load_lds_dwordx4 v[110:111], off
	v_lshl_add_u64 v[110:111], v[110:111], 0, s[78:79]
	s_add_i32 m0, s77, 98304
	s_nop 0
	global_load_lds_dwordx4 v[112:113], off
	v_lshl_add_u64 v[112:113], v[112:113], 0, s[78:79]
	s_add_i32 m0, s77, 99328
	s_nop 0
	global_load_lds_dwordx4 v[114:115], off
	v_lshl_add_u64 v[114:115], v[114:115], 0, s[78:79]
	s_waitcnt lgkmcnt(3)
	v_mfma_f32_16x16x32_bf16 v[120:123], v[152:155], v[160:163], v[120:123]
	v_mfma_f32_16x16x32_bf16 v[124:127], v[152:155], v[168:171], v[124:127]
	s_waitcnt lgkmcnt(0)
	v_mfma_f32_16x16x32_bf16 v[120:123], v[156:159], v[164:167], v[120:123]
	v_mfma_f32_16x16x32_bf16 v[124:127], v[156:159], v[172:175], v[124:127]
	s_waitcnt vmcnt(9)
	s_barrier
	ds_read_b128 v[128:131], v97
	ds_read_b128 v[136:139], v102 offset:0
	ds_read_b128 v[144:147], v102 offset:2048
	ds_read_b128 v[132:135], v189
	ds_read_b128 v[140:143], v194 offset:0
	ds_read_b128 v[148:151], v194 offset:2048
	s_add_i32 m0, s76, 0
	s_nop 0
	global_load_lds_dwordx4 v[110:111], off
	v_lshl_add_u64 v[110:111], v[110:111], 0, s[78:79]
	s_add_i32 m0, s77, 0
	s_nop 0
	global_load_lds_dwordx4 v[112:113], off
	v_lshl_add_u64 v[112:113], v[112:113], 0, s[78:79]
	s_add_i32 m0, s77, 1024
	s_nop 0
	global_load_lds_dwordx4 v[114:115], off
	v_lshl_add_u64 v[114:115], v[114:115], 0, s[78:79]
	s_waitcnt lgkmcnt(3)
	v_mfma_f32_16x16x32_bf16 v[120:123], v[128:131], v[136:139], v[120:123]
	v_mfma_f32_16x16x32_bf16 v[124:127], v[128:131], v[144:147], v[124:127]
	s_waitcnt lgkmcnt(0)
	v_mfma_f32_16x16x32_bf16 v[120:123], v[132:135], v[140:143], v[120:123]
	v_mfma_f32_16x16x32_bf16 v[124:127], v[132:135], v[148:151], v[124:127]
	s_waitcnt vmcnt(9)
	s_barrier
	ds_read_b128 v[152:155], v98
	ds_read_b128 v[160:163], v103 offset:0
	ds_read_b128 v[168:171], v103 offset:2048
	ds_read_b128 v[156:159], v190
	ds_read_b128 v[164:167], v195 offset:0
	ds_read_b128 v[172:175], v195 offset:2048
	s_add_i32 m0, s76, 24576
	s_nop 0
	global_load_lds_dwordx4 v[110:111], off
	v_lshl_add_u64 v[110:111], v[110:111], 0, s[78:79]
	s_add_i32 m0, s77, 24576
	s_nop 0
	global_load_lds_dwordx4 v[112:113], off
	v_lshl_add_u64 v[112:113], v[112:113], 0, s[78:79]
	s_add_i32 m0, s77, 25600
	s_nop 0
	global_load_lds_dwordx4 v[114:115], off
	v_lshl_add_u64 v[114:115], v[114:115], 0, s[78:79]
	s_waitcnt lgkmcnt(3)
	v_mfma_f32_16x16x32_bf16 v[120:123], v[152:155], v[160:163], v[120:123]
	v_mfma_f32_16x16x32_bf16 v[124:127], v[152:155], v[168:171], v[124:127]
	s_waitcnt lgkmcnt(0)
	v_mfma_f32_16x16x32_bf16 v[120:123], v[156:159], v[164:167], v[120:123]
	v_mfma_f32_16x16x32_bf16 v[124:127], v[156:159], v[172:175], v[124:127]
	s_waitcnt vmcnt(9)
	s_barrier
	ds_read_b128 v[128:131], v99
	ds_read_b128 v[136:139], v104 offset:0
	ds_read_b128 v[144:147], v104 offset:2048
	ds_read_b128 v[132:135], v191
	ds_read_b128 v[140:143], v196 offset:0
	ds_read_b128 v[148:151], v196 offset:2048
	s_waitcnt lgkmcnt(3)
	v_mfma_f32_16x16x32_bf16 v[120:123], v[128:131], v[136:139], v[120:123]
	v_mfma_f32_16x16x32_bf16 v[124:127], v[128:131], v[144:147], v[124:127]
	s_waitcnt lgkmcnt(0)
	v_mfma_f32_16x16x32_bf16 v[120:123], v[132:135], v[140:143], v[120:123]
	v_mfma_f32_16x16x32_bf16 v[124:127], v[132:135], v[148:151], v[124:127]
	s_waitcnt vmcnt(6)
	s_barrier
	ds_read_b128 v[152:155], v100
	ds_read_b128 v[160:163], v105 offset:0
	ds_read_b128 v[168:171], v105 offset:2048
	ds_read_b128 v[156:159], v192
	ds_read_b128 v[164:167], v197 offset:0
	ds_read_b128 v[172:175], v197 offset:2048
	s_waitcnt lgkmcnt(3)
	v_mfma_f32_16x16x32_bf16 v[120:123], v[152:155], v[160:163], v[120:123]
	v_mfma_f32_16x16x32_bf16 v[124:127], v[152:155], v[168:171], v[124:127]
	s_waitcnt lgkmcnt(0)
	v_mfma_f32_16x16x32_bf16 v[120:123], v[156:159], v[164:167], v[120:123]
	v_mfma_f32_16x16x32_bf16 v[124:127], v[156:159], v[172:175], v[124:127]
	s_waitcnt vmcnt(3)
	s_barrier
	ds_read_b128 v[128:131], v96
	ds_read_b128 v[136:139], v101 offset:0
	ds_read_b128 v[144:147], v101 offset:2048
	ds_read_b128 v[132:135], v188
	ds_read_b128 v[140:143], v193 offset:0
	ds_read_b128 v[148:151], v193 offset:2048
	s_waitcnt lgkmcnt(3)
	v_mfma_f32_16x16x32_bf16 v[120:123], v[128:131], v[136:139], v[120:123]
	v_mfma_f32_16x16x32_bf16 v[124:127], v[128:131], v[144:147], v[124:127]
	s_waitcnt lgkmcnt(0)
	v_mfma_f32_16x16x32_bf16 v[120:123], v[132:135], v[140:143], v[120:123]
	v_mfma_f32_16x16x32_bf16 v[124:127], v[132:135], v[148:151], v[124:127]
	s_waitcnt vmcnt(0)
	s_barrier
	ds_read_b128 v[152:155], v97
	ds_read_b128 v[160:163], v102 offset:0
	ds_read_b128 v[168:171], v102 offset:2048
	ds_read_b128 v[156:159], v189
	ds_read_b128 v[164:167], v194 offset:0
	ds_read_b128 v[172:175], v194 offset:2048
	s_waitcnt lgkmcnt(3)
	v_mfma_f32_16x16x32_bf16 v[120:123], v[152:155], v[160:163], v[120:123]
	v_mfma_f32_16x16x32_bf16 v[124:127], v[152:155], v[168:171], v[124:127]
	s_waitcnt lgkmcnt(0)
	v_mfma_f32_16x16x32_bf16 v[120:123], v[156:159], v[164:167], v[120:123]
	v_mfma_f32_16x16x32_bf16 v[124:127], v[156:159], v[172:175], v[124:127]
	s_barrier
	s_lshl_b32 s59, s82, 11
	s_lshl_b32 s62, s83, 1
	s_add_i32 s59, s59, s62
	s_add_u32 s60, s54, s59
	s_addc_u32 s61, s55, 0
	s_add_u32 s60, s60, 0x5700000
	s_addc_u32 s61, s61, 0
	v_lshl_add_u64 v[176:177], s[60:61], 0, v[106:107]
	s_mov_b32 s62, 0x1000
	s_mov_b32 s63, 0
	v_lshl_add_u64 v[178:179], v[176:177], 0, s[62:63]
	s_cmp_eq_u32 s70, 0
	s_cbranch_scc1 .Lsg_dn1_lo
	s_nop 4
	ds_write_b128 v109, v[120:123]
	ds_write_b128 v109, v[124:127] offset:1024
	s_waitcnt lgkmcnt(0)
	s_barrier
	s_branch .Lsg_dn1_done
